# P5 gate-mix hooks: NaN-canonicalising v_max x,x,x in front of each clamp removed (384 per tile hook pair), copies propagated
# baseline (speedup 1.0000x reference)
; __device__ __forceinline__ float bflo(unsigned w) { return __uint_as_float(w << 16); }
; __device__ __forceinline__ float bfhi(unsigned w) { return __uint_as_float(w & 0xffff0000u); }
;     static __device__ __forceinline__ float cl(float x) { return fminf(fmaxf(x, -30.f), 30.f); }
;     __device__ __forceinline__ void mid(f32x4 (&acc)[2][2][4][2], const Unit& u, int wr, int wc, int fr, int fq) const {
;         int fro = fr; asm volatile("" : "+v"(fro));
;         const int row0 = u.pm * BM + wr * 64 + fro;
; #pragma unroll
;         for (int ai = 0; ai < 2; ++ai)
; #pragma unroll
;             for (int m = 0; m < 4; ++m) { const size_t row = (size_t)(row0 + ai * HALF + m * 16);
; #pragma unroll
;                 for (int bj = 0; bj < 2; ++bj) { const int col = u.pn * BM + bj * HALF + wc * 32 + 8 * fq;
;                     const bf16_t* gp = gate + (size_t)(col >> 10) * SEC + row * 1024 + (col & 1023);
;                     const u32x4 ga = *(const u32x4*)gp, gb = *(const u32x4*)(gp + 2 * SEC);
;                     float ea[8] = {bflo(ga.x), bfhi(ga.x), bflo(ga.y), bfhi(ga.y), bflo(ga.z), bfhi(ga.z), bflo(ga.w), bfhi(ga.w)};
;                     float eb[8] = {bflo(gb.x), bfhi(gb.x), bflo(gb.y), bfhi(gb.y), bflo(gb.z), bfhi(gb.z), bflo(gb.w), bfhi(gb.w)};
;                     float r[8];
; #pragma unroll
;                     for (int e = 0; e < 8; ++e) r[e] = (1.f + __expf(-cl(eb[e]))) * __builtin_amdgcn_rcpf(1.f + __expf(-cl(ea[e])));
;                     acc[ai][bj][m][0][0] *= r[0]; acc[ai][bj][m][0][1] *= r[1]; acc[ai][bj][m][0][2] *= r[2]; acc[ai][bj][m][0][3] *= r[3];
;                     acc[ai][bj][m][1][0] *= r[4]; acc[ai][bj][m][1][1] *= r[5]; acc[ai][bj][m][1][2] *= r[6]; acc[ai][bj][m][1][3] *= r[7]; }
;                 if (m == 3) __builtin_amdgcn_sched_barrier(0); }
.LBB0_628:
	s_cmpk_lg_i32 s50, 0x800
	s_cbranch_scc1 .LBB0_627
	s_nop 0
	v_add_u32_e32 v2, s92, v154
	v_ashrrev_i32_e32 v3, 31, v2
	v_lshlrev_b64 v[2:3], 11, v[2:3]
	v_lshl_add_u64 v[2:3], v[148:149], 0, v[2:3]
	global_load_dwordx4 v[162:165], v[2:3], off
	v_add_co_u32_e32 v174, vcc, 0x8000000, v2
	s_waitcnt vmcnt(0)
	v_and_b32_e32 v161, 0xffff0000, v162
	v_addc_co_u32_e32 v175, vcc, 0, v3, vcc
	global_load_dwordx4 v[166:169], v[174:175], off
	global_load_dwordx4 v[170:173], v[2:3], off offset:256
	s_nop 0
	global_load_dwordx4 v[174:177], v[174:175], off offset:256
	v_lshlrev_b32_e32 v0, 16, v162
	v_lshlrev_b32_e32 v162, 16, v163
	v_and_b32_e32 v163, 0xffff0000, v163
	v_lshlrev_b32_e32 v178, 16, v164
	v_and_b32_e32 v164, 0xffff0000, v164
	v_med3_f32 v161, v161, s73, v159
	v_lshlrev_b32_e32 v179, 16, v165
	v_and_b32_e32 v183, 0xffff0000, v165
	v_mov_b32_e32 v165, v178
	v_med3_f32 v0, v0, s73, v159
	v_mul_f32_e32 v161, 0xbfb8aa3b, v161
	v_mov_b32_e32 v178, v179
	v_med3_f32 v162, v162, s73, v159
	v_med3_f32 v163, v163, s73, v159
	v_med3_f32 v165, v165, s73, v159
	v_med3_f32 v164, v164, s73, v159
	v_mul_f32_e32 v0, 0xbfb8aa3b, v0
	v_exp_f32_e32 v161, v161
	v_mul_f32_e32 v162, 0xbfb8aa3b, v162
	v_mul_f32_e32 v163, 0xbfb8aa3b, v163
	v_mul_f32_e32 v165, 0xbfb8aa3b, v165
	v_mul_f32_e32 v164, 0xbfb8aa3b, v164
	v_exp_f32_e32 v0, v0
	v_exp_f32_e32 v184, v163
	v_add_f32_e32 v161, 1.0, v161
	v_add_f32_e32 v0, 1.0, v0
	s_waitcnt vmcnt(2)
	v_lshlrev_b32_e32 v179, 16, v166
	v_lshlrev_b32_e32 v180, 16, v167
	v_lshlrev_b32_e32 v181, 16, v168
	v_and_b32_e32 v168, 0xffff0000, v168
	v_and_b32_e32 v167, 0xffff0000, v167
	v_lshlrev_b32_e32 v182, 16, v169
	v_and_b32_e32 v185, 0xffff0000, v169
	v_med3_f32 v169, v178, s73, v159
	v_mov_b32_e32 v178, v179
	v_mov_b32_e32 v179, v180
	v_mov_b32_e32 v180, v181
	v_and_b32_e32 v166, 0xffff0000, v166
	v_exp_f32_e32 v181, v162
	v_med3_f32 v163, v180, s73, v159
	v_exp_f32_e32 v180, v165
	v_med3_f32 v165, v168, s73, v159
	v_exp_f32_e32 v168, v164
	v_mul_f32_e32 v169, 0xbfb8aa3b, v169
	v_med3_f32 v162, v167, s73, v159
	v_med3_f32 v178, v178, s73, v159
	v_med3_f32 v166, v166, s73, v159
	v_med3_f32 v179, v179, s73, v159
	v_exp_f32_e32 v186, v169
	v_mul_f32_e32 v169, 0xbfb8aa3b, v162
	v_mul_f32_e32 v164, 0xbfb8aa3b, v178
	v_mul_f32_e32 v166, 0xbfb8aa3b, v166
	v_mul_f32_e32 v167, 0xbfb8aa3b, v179
	v_mul_f32_e32 v178, 0xbfb8aa3b, v163
	v_mul_f32_e32 v179, 0xbfb8aa3b, v165
	v_exp_f32_e32 v165, v169
	v_rcp_f32_e32 v169, v161
	v_exp_f32_e32 v163, v166
	v_exp_f32_e32 v166, v178
	v_add_f32_e32 v178, 1.0, v181
	v_add_f32_e32 v181, 1.0, v168
	v_rcp_f32_e32 v168, v0
	v_med3_f32 v0, v182, s73, v159
	v_med3_f32 v161, v183, s73, v159
	v_mul_f32_e32 v0, 0xbfb8aa3b, v0
	v_mul_f32_e32 v161, 0xbfb8aa3b, v161
	v_exp_f32_e32 v182, v0
	v_add_f32_e32 v0, 1.0, v186
	v_exp_f32_e32 v161, v161
	v_exp_f32_e32 v162, v164
	v_exp_f32_e32 v164, v167
	v_exp_f32_e32 v167, v179
	v_add_f32_e32 v179, 1.0, v184
	v_rcp_f32_e32 v184, v0
	v_med3_f32 v0, v185, s73, v159
	v_mul_f32_e32 v0, 0xbfb8aa3b, v0
	v_exp_f32_e32 v183, v0
	v_add_f32_e32 v0, 1.0, v161
	v_rcp_f32_e32 v185, v0
	v_pk_add_f32 v[162:163], v[162:163], 1.0 op_sel_hi:[1,0]
	s_waitcnt vmcnt(1)
	v_lshlrev_b32_e32 v0, 16, v170
	v_pk_mul_f32 v[162:163], v[162:163], v[168:169]
	v_pk_mul_f32 v[128:129], v[128:129], v[162:163]
	v_pk_add_f32 v[162:163], v[182:183], 1.0 op_sel_hi:[1,0]
	v_med3_f32 v0, v0, s73, v159
	v_rcp_f32_e32 v178, v178
	v_rcp_f32_e32 v179, v179
	v_pk_mul_f32 v[162:163], v[162:163], v[184:185]
	v_mul_f32_e32 v0, 0xbfb8aa3b, v0
	v_add_f32_e32 v180, 1.0, v180
	v_pk_mul_f32 v[126:127], v[126:127], v[162:163]
	s_waitcnt vmcnt(0)
	v_lshlrev_b32_e32 v162, 16, v174
	v_exp_f32_e32 v0, v0
	v_rcp_f32_e32 v180, v180
	v_rcp_f32_e32 v181, v181
	v_pk_add_f32 v[164:165], v[164:165], 1.0 op_sel_hi:[1,0]
	v_med3_f32 v162, v162, s73, v159
	v_pk_mul_f32 v[164:165], v[164:165], v[178:179]
	v_mul_f32_e32 v162, 0xbfb8aa3b, v162
	v_pk_mul_f32 v[130:131], v[130:131], v[164:165]
	v_pk_add_f32 v[164:165], v[166:167], 1.0 op_sel_hi:[1,0]
	v_and_b32_e32 v161, 0xffff0000, v170
	v_and_b32_e32 v163, 0xffff0000, v174
	v_exp_f32_e32 v170, v162
	v_add_f32_e32 v0, 1.0, v0
	v_add_co_u32_e32 v162, vcc, s71, v2
	v_pk_mul_f32 v[164:165], v[164:165], v[180:181]
	v_lshlrev_b32_e32 v180, 16, v172
	v_and_b32_e32 v181, 0xffff0000, v172
	v_rcp_f32_e32 v172, v0
	v_mov_b32_e32 v0, v163
	v_addc_co_u32_e32 v163, vcc, 0, v3, vcc
	v_pk_mul_f32 v[124:125], v[124:125], v[164:165]
	global_load_dwordx4 v[162:165], v[162:163], off
	v_med3_f32 v161, v161, s73, v159
	v_mul_f32_e32 v161, 0xbfb8aa3b, v161
	v_exp_f32_e32 v161, v161
	v_med3_f32 v0, v0, s73, v159
	v_lshlrev_b32_e32 v166, 16, v171
	v_mul_f32_e32 v0, 0xbfb8aa3b, v0
	v_and_b32_e32 v179, 0xffff0000, v171
	v_exp_f32_e32 v171, v0
	v_add_f32_e32 v0, 1.0, v161
	v_add_co_u32_e32 v174, vcc, s74, v2
	v_lshlrev_b32_e32 v167, 16, v175
	v_and_b32_e32 v182, 0xffff0000, v175
	v_med3_f32 v161, v166, s73, v159
	v_addc_co_u32_e32 v175, vcc, 0, v3, vcc
	v_lshlrev_b32_e32 v184, 16, v173
	v_and_b32_e32 v185, 0xffff0000, v173
	v_rcp_f32_e32 v173, v0
	v_mov_b32_e32 v0, v167
	v_mul_f32_e32 v161, 0xbfb8aa3b, v161
	global_load_dwordx4 v[166:169], v[174:175], off
	v_exp_f32_e32 v161, v161
	v_med3_f32 v0, v0, s73, v159
	v_mul_f32_e32 v0, 0xbfb8aa3b, v0
	v_lshlrev_b32_e32 v183, 16, v176
	v_and_b32_e32 v186, 0xffff0000, v176
	v_exp_f32_e32 v176, v0
	v_add_f32_e32 v0, 1.0, v161
	v_med3_f32 v161, v179, s73, v159
	v_mul_f32_e32 v161, 0xbfb8aa3b, v161
	v_exp_f32_e32 v161, v161
	v_rcp_f32_e32 v178, v0
	v_med3_f32 v0, v182, s73, v159
	v_mul_f32_e32 v0, 0xbfb8aa3b, v0
	v_lshlrev_b32_e32 v187, 16, v177
	v_and_b32_e32 v188, 0xffff0000, v177
; __device__ __forceinline__ float bflo(unsigned w) { return __uint_as_float(w << 16); }
; __device__ __forceinline__ float bfhi(unsigned w) { return __uint_as_float(w & 0xffff0000u); }
;     static __device__ __forceinline__ float cl(float x) { return fminf(fmaxf(x, -30.f), 30.f); }
;     __device__ __forceinline__ void mid(f32x4 (&acc)[2][2][4][2], const Unit& u, int wr, int wc, int fr, int fq) const {
;     ...
;             for (int m = 0; m < 4; ++m) { const size_t row = (size_t)(row0 + ai * HALF + m * 16);
; #pragma unroll
;                 for (int bj = 0; bj < 2; ++bj) { const int col = u.pn * BM + bj * HALF + wc * 32 + 8 * fq;
;                     const bf16_t* gp = gate + (size_t)(col >> 10) * SEC + row * 1024 + (col & 1023);
;                     const u32x4 ga = *(const u32x4*)gp, gb = *(const u32x4*)(gp + 2 * SEC);
;                     float ea[8] = {bflo(ga.x), bfhi(ga.x), bflo(ga.y), bfhi(ga.y), bflo(ga.z), bfhi(ga.z), bflo(ga.w), bfhi(ga.w)};
;                     float eb[8] = {bflo(gb.x), bfhi(gb.x), bflo(gb.y), bfhi(gb.y), bflo(gb.z), bfhi(gb.z), bflo(gb.w), bfhi(gb.w)};
;                     float r[8];
; #pragma unroll
;                     for (int e = 0; e < 8; ++e) r[e] = (1.f + __expf(-cl(eb[e]))) * __builtin_amdgcn_rcpf(1.f + __expf(-cl(ea[e])));
;                     acc[ai][bj][m][0][0] *= r[0]; acc[ai][bj][m][0][1] *= r[1]; acc[ai][bj][m][0][2] *= r[2]; acc[ai][bj][m][0][3] *= r[3];
;                     acc[ai][bj][m][1][0] *= r[4]; acc[ai][bj][m][1][1] *= r[5]; acc[ai][bj][m][1][2] *= r[6]; acc[ai][bj][m][1][3] *= r[7]; }
	v_exp_f32_e32 v177, v0
	v_add_f32_e32 v0, 1.0, v161
	v_med3_f32 v161, v180, s73, v159
	v_mul_f32_e32 v161, 0xbfb8aa3b, v161
	v_exp_f32_e32 v161, v161
	v_rcp_f32_e32 v179, v0
	v_med3_f32 v0, v183, s73, v159
	v_mul_f32_e32 v0, 0xbfb8aa3b, v0
	v_exp_f32_e32 v180, v0
	v_add_f32_e32 v0, 1.0, v161
	v_med3_f32 v161, v181, s73, v159
	v_mul_f32_e32 v161, 0xbfb8aa3b, v161
	v_exp_f32_e32 v161, v161
	v_rcp_f32_e32 v182, v0
	v_med3_f32 v0, v186, s73, v159
	v_mul_f32_e32 v0, 0xbfb8aa3b, v0
	v_exp_f32_e32 v181, v0
	v_add_f32_e32 v0, 1.0, v161
	v_med3_f32 v161, v184, s73, v159
	v_mul_f32_e32 v161, 0xbfb8aa3b, v161
	v_exp_f32_e32 v161, v161
	v_rcp_f32_e32 v183, v0
	v_med3_f32 v0, v187, s73, v159
	v_mul_f32_e32 v0, 0xbfb8aa3b, v0
	v_exp_f32_e32 v184, v0
	v_add_f32_e32 v0, 1.0, v161
	v_med3_f32 v161, v185, s73, v159
	v_mul_f32_e32 v161, 0xbfb8aa3b, v161
	v_exp_f32_e32 v161, v161
	v_rcp_f32_e32 v186, v0
	v_med3_f32 v0, v188, s73, v159
	v_mul_f32_e32 v0, 0xbfb8aa3b, v0
	v_exp_f32_e32 v185, v0
	v_add_f32_e32 v0, 1.0, v161
	v_rcp_f32_e32 v187, v0
	v_pk_add_f32 v[170:171], v[170:171], 1.0 op_sel_hi:[1,0]
	v_pk_add_f32 v[176:177], v[176:177], 1.0 op_sel_hi:[1,0]
	v_pk_mul_f32 v[170:171], v[170:171], v[172:173]
	v_pk_mul_f32 v[172:173], v[176:177], v[178:179]
	v_pk_mul_f32 v[120:121], v[120:121], v[170:171]
	v_pk_add_f32 v[170:171], v[184:185], 1.0 op_sel_hi:[1,0]
	v_pk_mul_f32 v[122:123], v[122:123], v[172:173]
	v_pk_add_f32 v[172:173], v[180:181], 1.0 op_sel_hi:[1,0]
	v_pk_mul_f32 v[170:171], v[170:171], v[186:187]
	v_pk_mul_f32 v[172:173], v[172:173], v[182:183]
	v_pk_mul_f32 v[118:119], v[118:119], v[170:171]
	v_lshl_add_u64 v[170:171], v[2:3], 0, s[12:13]
	v_pk_mul_f32 v[116:117], v[116:117], v[172:173]
	global_load_dwordx4 v[170:173], v[170:171], off offset:256
	s_waitcnt vmcnt(2)
	v_lshlrev_b32_e32 v0, 16, v162
	v_and_b32_e32 v161, 0xffff0000, v162
	v_lshlrev_b32_e32 v176, 16, v163
	v_and_b32_e32 v177, 0xffff0000, v163
	v_lshlrev_b32_e32 v178, 16, v164
	v_and_b32_e32 v179, 0xffff0000, v164
	v_lshlrev_b32_e32 v182, 16, v165
	v_and_b32_e32 v183, 0xffff0000, v165
	global_load_dwordx4 v[162:165], v[174:175], off offset:256
	v_med3_f32 v0, v0, s73, v159
	v_mul_f32_e32 v0, 0xbfb8aa3b, v0
	v_exp_f32_e32 v0, v0
	v_med3_f32 v161, v161, s73, v159
	v_mul_f32_e32 v161, 0xbfb8aa3b, v161
	s_waitcnt vmcnt(2)
	v_and_b32_e32 v175, 0xffff0000, v166
	v_add_f32_e32 v0, 1.0, v0
	v_exp_f32_e32 v161, v161
	v_lshlrev_b32_e32 v184, 16, v168
	v_and_b32_e32 v185, 0xffff0000, v168
	v_rcp_f32_e32 v168, v0
	v_med3_f32 v0, v175, s73, v159
	v_mul_f32_e32 v0, 0xbfb8aa3b, v0
	v_lshlrev_b32_e32 v180, 16, v167
	v_and_b32_e32 v181, 0xffff0000, v167
	v_exp_f32_e32 v167, v0
	v_add_f32_e32 v0, 1.0, v161
	v_med3_f32 v161, v176, s73, v159
	v_mul_f32_e32 v161, 0xbfb8aa3b, v161
	v_exp_f32_e32 v161, v161
	v_lshlrev_b32_e32 v186, 16, v169
	v_and_b32_e32 v187, 0xffff0000, v169
	v_rcp_f32_e32 v169, v0
	v_med3_f32 v0, v180, s73, v159
	v_lshlrev_b32_e32 v174, 16, v166
	v_mul_f32_e32 v0, 0xbfb8aa3b, v0
	v_mov_b32_e32 v166, v174
	v_exp_f32_e32 v174, v0
	v_add_f32_e32 v0, 1.0, v161
	v_med3_f32 v161, v177, s73, v159
	v_mul_f32_e32 v161, 0xbfb8aa3b, v161
	v_exp_f32_e32 v161, v161
	v_rcp_f32_e32 v176, v0
	v_med3_f32 v0, v181, s73, v159
	v_mul_f32_e32 v0, 0xbfb8aa3b, v0
	v_exp_f32_e32 v175, v0
	v_add_f32_e32 v0, 1.0, v161
	v_med3_f32 v161, v178, s73, v159
	v_mul_f32_e32 v161, 0xbfb8aa3b, v161
	v_exp_f32_e32 v161, v161
	v_rcp_f32_e32 v177, v0
	v_med3_f32 v0, v184, s73, v159
	v_mul_f32_e32 v0, 0xbfb8aa3b, v0
	v_exp_f32_e32 v178, v0
	v_add_f32_e32 v0, 1.0, v161
	v_med3_f32 v161, v179, s73, v159
	v_mul_f32_e32 v161, 0xbfb8aa3b, v161
	v_exp_f32_e32 v161, v161
	v_rcp_f32_e32 v180, v0
	v_med3_f32 v0, v185, s73, v159
	v_mul_f32_e32 v0, 0xbfb8aa3b, v0
	v_exp_f32_e32 v179, v0
	v_add_f32_e32 v0, 1.0, v161
	v_med3_f32 v161, v182, s73, v159
	v_mul_f32_e32 v161, 0xbfb8aa3b, v161
	v_exp_f32_e32 v161, v161
	v_rcp_f32_e32 v181, v0
	v_med3_f32 v0, v186, s73, v159
	v_mul_f32_e32 v0, 0xbfb8aa3b, v0
	v_exp_f32_e32 v182, v0
	v_add_f32_e32 v0, 1.0, v161
	v_med3_f32 v161, v183, s73, v159
	v_mul_f32_e32 v161, 0xbfb8aa3b, v161
	v_exp_f32_e32 v161, v161
	v_med3_f32 v166, v166, s73, v159
	v_rcp_f32_e32 v184, v0
	v_mul_f32_e32 v166, 0xbfb8aa3b, v166
	v_med3_f32 v0, v187, s73, v159
	v_exp_f32_e32 v166, v166
	v_mul_f32_e32 v0, 0xbfb8aa3b, v0
	v_exp_f32_e32 v183, v0
	v_add_f32_e32 v0, 1.0, v161
	v_rcp_f32_e32 v185, v0
	s_waitcnt vmcnt(1)
	v_lshlrev_b32_e32 v0, 16, v170
	v_pk_add_f32 v[166:167], v[166:167], 1.0 op_sel_hi:[1,0]
	v_med3_f32 v0, v0, s73, v159
	v_pk_add_f32 v[174:175], v[174:175], 1.0 op_sel_hi:[1,0]
	v_pk_mul_f32 v[166:167], v[166:167], v[168:169]
	v_mul_f32_e32 v0, 0xbfb8aa3b, v0
	v_pk_mul_f32 v[168:169], v[174:175], v[176:177]
	v_pk_mul_f32 v[112:113], v[112:113], v[166:167]
	v_pk_add_f32 v[166:167], v[182:183], 1.0 op_sel_hi:[1,0]
	v_exp_f32_e32 v0, v0
	v_pk_mul_f32 v[114:115], v[114:115], v[168:169]
	v_pk_add_f32 v[168:169], v[178:179], 1.0 op_sel_hi:[1,0]
	v_pk_mul_f32 v[166:167], v[166:167], v[184:185]
	v_pk_mul_f32 v[168:169], v[168:169], v[180:181]
	v_pk_mul_f32 v[110:111], v[110:111], v[166:167]
	s_waitcnt vmcnt(0)
; __device__ __forceinline__ float bflo(unsigned w) { return __uint_as_float(w << 16); }
; __device__ __forceinline__ float bfhi(unsigned w) { return __uint_as_float(w & 0xffff0000u); }
;     static __device__ __forceinline__ float cl(float x) { return fminf(fmaxf(x, -30.f), 30.f); }
;     __device__ __forceinline__ void mid(f32x4 (&acc)[2][2][4][2], const Unit& u, int wr, int wc, int fr, int fq) const {
;     ...
;             for (int m = 0; m < 4; ++m) { const size_t row = (size_t)(row0 + ai * HALF + m * 16);
; #pragma unroll
;                 for (int bj = 0; bj < 2; ++bj) { const int col = u.pn * BM + bj * HALF + wc * 32 + 8 * fq;
;                     const bf16_t* gp = gate + (size_t)(col >> 10) * SEC + row * 1024 + (col & 1023);
;                     const u32x4 ga = *(const u32x4*)gp, gb = *(const u32x4*)(gp + 2 * SEC);
;                     float ea[8] = {bflo(ga.x), bfhi(ga.x), bflo(ga.y), bfhi(ga.y), bflo(ga.z), bfhi(ga.z), bflo(ga.w), bfhi(ga.w)};
;                     float eb[8] = {bflo(gb.x), bfhi(gb.x), bflo(gb.y), bfhi(gb.y), bflo(gb.z), bfhi(gb.z), bflo(gb.w), bfhi(gb.w)};
;                     float r[8];
; #pragma unroll
;                     for (int e = 0; e < 8; ++e) r[e] = (1.f + __expf(-cl(eb[e]))) * __builtin_amdgcn_rcpf(1.f + __expf(-cl(ea[e])));
;                     acc[ai][bj][m][0][0] *= r[0]; acc[ai][bj][m][0][1] *= r[1]; acc[ai][bj][m][0][2] *= r[2]; acc[ai][bj][m][0][3] *= r[3];
;                     acc[ai][bj][m][1][0] *= r[4]; acc[ai][bj][m][1][1] *= r[5]; acc[ai][bj][m][1][2] *= r[6]; acc[ai][bj][m][1][3] *= r[7]; }
	v_lshlrev_b32_e32 v167, 16, v162
	v_pk_mul_f32 v[108:109], v[108:109], v[168:169]
	v_lshlrev_b32_e32 v168, 16, v163
	v_and_b32_e32 v179, 0xffff0000, v163
	v_and_b32_e32 v162, 0xffff0000, v162
	v_med3_f32 v163, v167, s73, v159
	v_add_f32_e32 v0, 1.0, v0
	v_lshlrev_b32_e32 v180, 16, v172
	v_and_b32_e32 v181, 0xffff0000, v172
	v_mul_f32_e32 v163, 0xbfb8aa3b, v163
	v_rcp_f32_e32 v172, v0
	v_mov_b32_e32 v0, v162
	v_add_co_u32_e32 v162, vcc, s64, v2
	v_and_b32_e32 v161, 0xffff0000, v170
	v_exp_f32_e32 v170, v163
	v_addc_co_u32_e32 v163, vcc, 0, v3, vcc
	v_lshlrev_b32_e32 v182, 16, v164
	v_and_b32_e32 v183, 0xffff0000, v164
	v_lshlrev_b32_e32 v186, 16, v165
	v_and_b32_e32 v187, 0xffff0000, v165
	global_load_dwordx4 v[162:165], v[162:163], off
	v_med3_f32 v161, v161, s73, v159
	v_mul_f32_e32 v161, 0xbfb8aa3b, v161
	v_exp_f32_e32 v161, v161
	v_med3_f32 v0, v0, s73, v159
	v_lshlrev_b32_e32 v166, 16, v171
	v_mul_f32_e32 v0, 0xbfb8aa3b, v0
	v_and_b32_e32 v177, 0xffff0000, v171
	v_exp_f32_e32 v171, v0
	v_add_f32_e32 v0, 1.0, v161
	v_add_co_u32_e32 v174, vcc, s75, v2
	v_med3_f32 v161, v166, s73, v159
	s_nop 0
	v_addc_co_u32_e32 v175, vcc, 0, v3, vcc
	v_lshlrev_b32_e32 v184, 16, v173
	v_and_b32_e32 v185, 0xffff0000, v173
	v_rcp_f32_e32 v173, v0
	v_mov_b32_e32 v0, v168
	v_mul_f32_e32 v161, 0xbfb8aa3b, v161
	global_load_dwordx4 v[166:169], v[174:175], off
	v_exp_f32_e32 v161, v161
	v_med3_f32 v0, v0, s73, v159
	v_mul_f32_e32 v0, 0xbfb8aa3b, v0
	v_exp_f32_e32 v176, v0
	v_add_f32_e32 v0, 1.0, v161
	v_med3_f32 v161, v177, s73, v159
	v_mul_f32_e32 v161, 0xbfb8aa3b, v161
	v_exp_f32_e32 v161, v161
	v_rcp_f32_e32 v178, v0
	v_med3_f32 v0, v179, s73, v159
	v_mul_f32_e32 v0, 0xbfb8aa3b, v0
	v_exp_f32_e32 v177, v0
	v_add_f32_e32 v0, 1.0, v161
	v_med3_f32 v161, v180, s73, v159
	v_mul_f32_e32 v161, 0xbfb8aa3b, v161
	v_exp_f32_e32 v161, v161
	v_rcp_f32_e32 v179, v0
	v_med3_f32 v0, v182, s73, v159
	v_mul_f32_e32 v0, 0xbfb8aa3b, v0
	v_exp_f32_e32 v180, v0
	v_add_f32_e32 v0, 1.0, v161
	v_med3_f32 v161, v181, s73, v159
	v_mul_f32_e32 v161, 0xbfb8aa3b, v161
	v_exp_f32_e32 v161, v161
	v_rcp_f32_e32 v182, v0
	v_med3_f32 v0, v183, s73, v159
	v_mul_f32_e32 v0, 0xbfb8aa3b, v0
	v_exp_f32_e32 v181, v0
	v_add_f32_e32 v0, 1.0, v161
	v_med3_f32 v161, v184, s73, v159
	v_mul_f32_e32 v161, 0xbfb8aa3b, v161
	v_exp_f32_e32 v161, v161
	v_rcp_f32_e32 v183, v0
	v_med3_f32 v0, v186, s73, v159
	v_mul_f32_e32 v0, 0xbfb8aa3b, v0
	v_exp_f32_e32 v184, v0
	v_add_f32_e32 v0, 1.0, v161
	v_med3_f32 v161, v185, s73, v159
	v_mul_f32_e32 v161, 0xbfb8aa3b, v161
	v_exp_f32_e32 v161, v161
	v_rcp_f32_e32 v186, v0
	v_med3_f32 v0, v187, s73, v159
	v_mul_f32_e32 v0, 0xbfb8aa3b, v0
	v_exp_f32_e32 v185, v0
	v_add_f32_e32 v0, 1.0, v161
	v_rcp_f32_e32 v187, v0
	v_pk_add_f32 v[170:171], v[170:171], 1.0 op_sel_hi:[1,0]
	v_pk_add_f32 v[176:177], v[176:177], 1.0 op_sel_hi:[1,0]
	v_pk_mul_f32 v[170:171], v[170:171], v[172:173]
	v_pk_mul_f32 v[172:173], v[176:177], v[178:179]
	v_pk_mul_f32 v[104:105], v[104:105], v[170:171]
	v_pk_add_f32 v[170:171], v[184:185], 1.0 op_sel_hi:[1,0]
	v_pk_mul_f32 v[106:107], v[106:107], v[172:173]
	v_pk_add_f32 v[172:173], v[180:181], 1.0 op_sel_hi:[1,0]
	v_pk_mul_f32 v[170:171], v[170:171], v[186:187]
	v_pk_mul_f32 v[172:173], v[172:173], v[182:183]
	v_pk_mul_f32 v[102:103], v[102:103], v[170:171]
	v_lshl_add_u64 v[170:171], v[2:3], 0, s[14:15]
	v_pk_mul_f32 v[100:101], v[100:101], v[172:173]
	global_load_dwordx4 v[170:173], v[170:171], off offset:256
	s_waitcnt vmcnt(2)
	v_lshlrev_b32_e32 v0, 16, v162
	v_and_b32_e32 v161, 0xffff0000, v162
	v_lshlrev_b32_e32 v176, 16, v163
	v_and_b32_e32 v177, 0xffff0000, v163
	v_lshlrev_b32_e32 v178, 16, v164
	v_and_b32_e32 v179, 0xffff0000, v164
	v_lshlrev_b32_e32 v182, 16, v165
	v_and_b32_e32 v183, 0xffff0000, v165
	global_load_dwordx4 v[162:165], v[174:175], off offset:256
	v_med3_f32 v0, v0, s73, v159
	v_mul_f32_e32 v0, 0xbfb8aa3b, v0
	v_exp_f32_e32 v0, v0
	v_med3_f32 v161, v161, s73, v159
	v_mul_f32_e32 v161, 0xbfb8aa3b, v161
	s_waitcnt vmcnt(2)
	v_and_b32_e32 v175, 0xffff0000, v166
	v_add_f32_e32 v0, 1.0, v0
	v_exp_f32_e32 v161, v161
	v_lshlrev_b32_e32 v184, 16, v168
	v_and_b32_e32 v185, 0xffff0000, v168
	v_rcp_f32_e32 v168, v0
	v_med3_f32 v0, v175, s73, v159
	v_mul_f32_e32 v0, 0xbfb8aa3b, v0
	v_lshlrev_b32_e32 v180, 16, v167
	v_and_b32_e32 v181, 0xffff0000, v167
	v_exp_f32_e32 v167, v0
	v_add_f32_e32 v0, 1.0, v161
	v_med3_f32 v161, v176, s73, v159
	v_mul_f32_e32 v161, 0xbfb8aa3b, v161
	v_exp_f32_e32 v161, v161
	v_lshlrev_b32_e32 v186, 16, v169
	v_and_b32_e32 v187, 0xffff0000, v169
	v_rcp_f32_e32 v169, v0
	v_med3_f32 v0, v180, s73, v159
	v_lshlrev_b32_e32 v174, 16, v166
	v_mul_f32_e32 v0, 0xbfb8aa3b, v0
	v_mov_b32_e32 v166, v174
	v_exp_f32_e32 v174, v0
	v_add_f32_e32 v0, 1.0, v161
	v_med3_f32 v161, v177, s73, v159
	v_mul_f32_e32 v161, 0xbfb8aa3b, v161
	v_exp_f32_e32 v161, v161
	v_rcp_f32_e32 v176, v0
	v_med3_f32 v0, v181, s73, v159
	v_mul_f32_e32 v0, 0xbfb8aa3b, v0
	v_exp_f32_e32 v175, v0
	v_add_f32_e32 v0, 1.0, v161
	v_med3_f32 v161, v178, s73, v159
	v_mul_f32_e32 v161, 0xbfb8aa3b, v161
	v_exp_f32_e32 v161, v161
	v_rcp_f32_e32 v177, v0
	v_med3_f32 v0, v184, s73, v159
	v_mul_f32_e32 v0, 0xbfb8aa3b, v0
	v_exp_f32_e32 v178, v0
	v_add_f32_e32 v0, 1.0, v161
	v_med3_f32 v161, v179, s73, v159
	v_mul_f32_e32 v161, 0xbfb8aa3b, v161
	v_exp_f32_e32 v161, v161
	v_rcp_f32_e32 v180, v0
	v_med3_f32 v0, v185, s73, v159
	v_mul_f32_e32 v0, 0xbfb8aa3b, v0
	v_exp_f32_e32 v179, v0
	v_add_f32_e32 v0, 1.0, v161
	v_med3_f32 v161, v182, s73, v159
	v_mul_f32_e32 v161, 0xbfb8aa3b, v161
	v_exp_f32_e32 v161, v161
	v_rcp_f32_e32 v181, v0
	v_med3_f32 v0, v186, s73, v159
	v_mul_f32_e32 v0, 0xbfb8aa3b, v0
	v_exp_f32_e32 v182, v0
	v_add_f32_e32 v0, 1.0, v161
	v_med3_f32 v161, v183, s73, v159
	v_mul_f32_e32 v161, 0xbfb8aa3b, v161
	v_exp_f32_e32 v161, v161
	v_med3_f32 v166, v166, s73, v159
	v_rcp_f32_e32 v184, v0
	v_mul_f32_e32 v166, 0xbfb8aa3b, v166
	v_med3_f32 v0, v187, s73, v159
	v_exp_f32_e32 v166, v166
	v_mul_f32_e32 v0, 0xbfb8aa3b, v0
	v_exp_f32_e32 v183, v0
	v_add_f32_e32 v0, 1.0, v161
	v_rcp_f32_e32 v185, v0
	s_waitcnt vmcnt(1)
; __device__ __forceinline__ float bflo(unsigned w) { return __uint_as_float(w << 16); }
; __device__ __forceinline__ float bfhi(unsigned w) { return __uint_as_float(w & 0xffff0000u); }
;     static __device__ __forceinline__ float cl(float x) { return fminf(fmaxf(x, -30.f), 30.f); }
;     __device__ __forceinline__ void mid(f32x4 (&acc)[2][2][4][2], const Unit& u, int wr, int wc, int fr, int fq) const {
;     ...
;             for (int m = 0; m < 4; ++m) { const size_t row = (size_t)(row0 + ai * HALF + m * 16);
; #pragma unroll
;                 for (int bj = 0; bj < 2; ++bj) { const int col = u.pn * BM + bj * HALF + wc * 32 + 8 * fq;
;                     const bf16_t* gp = gate + (size_t)(col >> 10) * SEC + row * 1024 + (col & 1023);
;                     const u32x4 ga = *(const u32x4*)gp, gb = *(const u32x4*)(gp + 2 * SEC);
;                     float ea[8] = {bflo(ga.x), bfhi(ga.x), bflo(ga.y), bfhi(ga.y), bflo(ga.z), bfhi(ga.z), bflo(ga.w), bfhi(ga.w)};
;                     float eb[8] = {bflo(gb.x), bfhi(gb.x), bflo(gb.y), bfhi(gb.y), bflo(gb.z), bfhi(gb.z), bflo(gb.w), bfhi(gb.w)};
;                     float r[8];
; #pragma unroll
;                     for (int e = 0; e < 8; ++e) r[e] = (1.f + __expf(-cl(eb[e]))) * __builtin_amdgcn_rcpf(1.f + __expf(-cl(ea[e])));
;                     acc[ai][bj][m][0][0] *= r[0]; acc[ai][bj][m][0][1] *= r[1]; acc[ai][bj][m][0][2] *= r[2]; acc[ai][bj][m][0][3] *= r[3];
;                     acc[ai][bj][m][1][0] *= r[4]; acc[ai][bj][m][1][1] *= r[5]; acc[ai][bj][m][1][2] *= r[6]; acc[ai][bj][m][1][3] *= r[7]; }
	v_lshlrev_b32_e32 v0, 16, v170
	v_pk_add_f32 v[166:167], v[166:167], 1.0 op_sel_hi:[1,0]
	v_med3_f32 v0, v0, s73, v159
	v_pk_add_f32 v[174:175], v[174:175], 1.0 op_sel_hi:[1,0]
	v_pk_mul_f32 v[166:167], v[166:167], v[168:169]
	v_mul_f32_e32 v0, 0xbfb8aa3b, v0
	v_pk_mul_f32 v[168:169], v[174:175], v[176:177]
	v_pk_mul_f32 v[96:97], v[96:97], v[166:167]
	v_pk_add_f32 v[166:167], v[182:183], 1.0 op_sel_hi:[1,0]
	v_exp_f32_e32 v0, v0
	v_pk_mul_f32 v[98:99], v[98:99], v[168:169]
	v_pk_add_f32 v[168:169], v[178:179], 1.0 op_sel_hi:[1,0]
	v_pk_mul_f32 v[166:167], v[166:167], v[184:185]
	v_pk_mul_f32 v[168:169], v[168:169], v[180:181]
	v_pk_mul_f32 v[94:95], v[94:95], v[166:167]
	s_waitcnt vmcnt(0)
	v_lshlrev_b32_e32 v167, 16, v162
	v_pk_mul_f32 v[92:93], v[92:93], v[168:169]
	v_lshlrev_b32_e32 v168, 16, v163
	v_and_b32_e32 v179, 0xffff0000, v163
	v_and_b32_e32 v162, 0xffff0000, v162
	v_med3_f32 v163, v167, s73, v159
	v_add_f32_e32 v0, 1.0, v0
	v_lshlrev_b32_e32 v180, 16, v172
	v_and_b32_e32 v181, 0xffff0000, v172
	v_mul_f32_e32 v163, 0xbfb8aa3b, v163
	v_rcp_f32_e32 v172, v0
	v_mov_b32_e32 v0, v162
	v_add_co_u32_e32 v162, vcc, s70, v2
	v_and_b32_e32 v161, 0xffff0000, v170
	v_exp_f32_e32 v170, v163
	v_addc_co_u32_e32 v163, vcc, 0, v3, vcc
	v_lshlrev_b32_e32 v182, 16, v164
	v_and_b32_e32 v183, 0xffff0000, v164
	v_lshlrev_b32_e32 v186, 16, v165
	v_and_b32_e32 v187, 0xffff0000, v165
	global_load_dwordx4 v[162:165], v[162:163], off
	v_med3_f32 v161, v161, s73, v159
	v_mul_f32_e32 v161, 0xbfb8aa3b, v161
	v_exp_f32_e32 v161, v161
	v_med3_f32 v0, v0, s73, v159
	v_lshlrev_b32_e32 v166, 16, v171
	v_mul_f32_e32 v0, 0xbfb8aa3b, v0
	v_and_b32_e32 v177, 0xffff0000, v171
	v_exp_f32_e32 v171, v0
	v_add_f32_e32 v0, 1.0, v161
	v_add_co_u32_e32 v174, vcc, s76, v2
	v_med3_f32 v161, v166, s73, v159
	s_nop 0
	v_addc_co_u32_e32 v175, vcc, 0, v3, vcc
	v_lshlrev_b32_e32 v184, 16, v173
	v_and_b32_e32 v185, 0xffff0000, v173
	v_rcp_f32_e32 v173, v0
	v_mov_b32_e32 v0, v168
	v_mul_f32_e32 v161, 0xbfb8aa3b, v161
	global_load_dwordx4 v[166:169], v[174:175], off
	v_exp_f32_e32 v161, v161
	v_med3_f32 v0, v0, s73, v159
	v_mul_f32_e32 v0, 0xbfb8aa3b, v0
	v_exp_f32_e32 v176, v0
	v_add_f32_e32 v0, 1.0, v161
	v_med3_f32 v161, v177, s73, v159
	v_mul_f32_e32 v161, 0xbfb8aa3b, v161
	v_exp_f32_e32 v161, v161
	v_rcp_f32_e32 v178, v0
	v_med3_f32 v0, v179, s73, v159
	v_mul_f32_e32 v0, 0xbfb8aa3b, v0
	v_exp_f32_e32 v177, v0
	v_add_f32_e32 v0, 1.0, v161
	v_med3_f32 v161, v180, s73, v159
	v_mul_f32_e32 v161, 0xbfb8aa3b, v161
	v_exp_f32_e32 v161, v161
	v_rcp_f32_e32 v179, v0
	v_med3_f32 v0, v182, s73, v159
	v_mul_f32_e32 v0, 0xbfb8aa3b, v0
	v_exp_f32_e32 v180, v0
	v_add_f32_e32 v0, 1.0, v161
	v_med3_f32 v161, v181, s73, v159
	v_mul_f32_e32 v161, 0xbfb8aa3b, v161
	v_exp_f32_e32 v161, v161
	v_rcp_f32_e32 v182, v0
	v_med3_f32 v0, v183, s73, v159
	v_mul_f32_e32 v0, 0xbfb8aa3b, v0
	v_exp_f32_e32 v181, v0
	v_add_f32_e32 v0, 1.0, v161
	v_med3_f32 v161, v184, s73, v159
	v_mul_f32_e32 v161, 0xbfb8aa3b, v161
	v_exp_f32_e32 v161, v161
	v_rcp_f32_e32 v183, v0
	v_med3_f32 v0, v186, s73, v159
	v_mul_f32_e32 v0, 0xbfb8aa3b, v0
	v_exp_f32_e32 v184, v0
	v_add_f32_e32 v0, 1.0, v161
	v_med3_f32 v161, v185, s73, v159
	v_mul_f32_e32 v161, 0xbfb8aa3b, v161
	v_exp_f32_e32 v161, v161
	v_rcp_f32_e32 v186, v0
	v_med3_f32 v0, v187, s73, v159
	v_mul_f32_e32 v0, 0xbfb8aa3b, v0
	v_exp_f32_e32 v185, v0
	v_add_f32_e32 v0, 1.0, v161
	v_rcp_f32_e32 v187, v0
	v_pk_add_f32 v[170:171], v[170:171], 1.0 op_sel_hi:[1,0]
	v_pk_add_f32 v[176:177], v[176:177], 1.0 op_sel_hi:[1,0]
	v_pk_mul_f32 v[170:171], v[170:171], v[172:173]
	v_pk_mul_f32 v[172:173], v[176:177], v[178:179]
	v_pk_mul_f32 v[88:89], v[88:89], v[170:171]
	v_pk_add_f32 v[170:171], v[184:185], 1.0 op_sel_hi:[1,0]
	v_pk_mul_f32 v[90:91], v[90:91], v[172:173]
	v_pk_add_f32 v[172:173], v[180:181], 1.0 op_sel_hi:[1,0]
	v_pk_mul_f32 v[170:171], v[170:171], v[186:187]
	v_pk_mul_f32 v[172:173], v[172:173], v[182:183]
	v_pk_mul_f32 v[86:87], v[86:87], v[170:171]
	v_lshl_add_u64 v[170:171], v[2:3], 0, s[16:17]
	v_pk_mul_f32 v[84:85], v[84:85], v[172:173]
	global_load_dwordx4 v[170:173], v[170:171], off offset:256
	s_waitcnt vmcnt(2)
	v_lshlrev_b32_e32 v0, 16, v162
	v_and_b32_e32 v161, 0xffff0000, v162
	v_lshlrev_b32_e32 v176, 16, v163
	v_and_b32_e32 v177, 0xffff0000, v163
	v_lshlrev_b32_e32 v178, 16, v164
	v_and_b32_e32 v179, 0xffff0000, v164
	v_lshlrev_b32_e32 v182, 16, v165
	v_and_b32_e32 v183, 0xffff0000, v165
	global_load_dwordx4 v[162:165], v[174:175], off offset:256
	v_med3_f32 v0, v0, s73, v159
	v_mul_f32_e32 v0, 0xbfb8aa3b, v0
	v_exp_f32_e32 v0, v0
	v_med3_f32 v161, v161, s73, v159
	v_mul_f32_e32 v161, 0xbfb8aa3b, v161
	s_waitcnt vmcnt(2)
; __device__ __forceinline__ float bflo(unsigned w) { return __uint_as_float(w << 16); }
; __device__ __forceinline__ float bfhi(unsigned w) { return __uint_as_float(w & 0xffff0000u); }
;     static __device__ __forceinline__ float cl(float x) { return fminf(fmaxf(x, -30.f), 30.f); }
;     __device__ __forceinline__ void mid(f32x4 (&acc)[2][2][4][2], const Unit& u, int wr, int wc, int fr, int fq) const {
;     ...
;             for (int m = 0; m < 4; ++m) { const size_t row = (size_t)(row0 + ai * HALF + m * 16);
; #pragma unroll
;                 for (int bj = 0; bj < 2; ++bj) { const int col = u.pn * BM + bj * HALF + wc * 32 + 8 * fq;
;                     const bf16_t* gp = gate + (size_t)(col >> 10) * SEC + row * 1024 + (col & 1023);
;                     const u32x4 ga = *(const u32x4*)gp, gb = *(const u32x4*)(gp + 2 * SEC);
;                     float ea[8] = {bflo(ga.x), bfhi(ga.x), bflo(ga.y), bfhi(ga.y), bflo(ga.z), bfhi(ga.z), bflo(ga.w), bfhi(ga.w)};
;                     float eb[8] = {bflo(gb.x), bfhi(gb.x), bflo(gb.y), bfhi(gb.y), bflo(gb.z), bfhi(gb.z), bflo(gb.w), bfhi(gb.w)};
;                     float r[8];
; #pragma unroll
;                     for (int e = 0; e < 8; ++e) r[e] = (1.f + __expf(-cl(eb[e]))) * __builtin_amdgcn_rcpf(1.f + __expf(-cl(ea[e])));
;                     acc[ai][bj][m][0][0] *= r[0]; acc[ai][bj][m][0][1] *= r[1]; acc[ai][bj][m][0][2] *= r[2]; acc[ai][bj][m][0][3] *= r[3];
;                     acc[ai][bj][m][1][0] *= r[4]; acc[ai][bj][m][1][1] *= r[5]; acc[ai][bj][m][1][2] *= r[6]; acc[ai][bj][m][1][3] *= r[7]; }
	v_and_b32_e32 v175, 0xffff0000, v166
	v_add_f32_e32 v0, 1.0, v0
	v_exp_f32_e32 v161, v161
	v_lshlrev_b32_e32 v184, 16, v168
	v_and_b32_e32 v185, 0xffff0000, v168
	v_rcp_f32_e32 v168, v0
	v_med3_f32 v0, v175, s73, v159
	v_mul_f32_e32 v0, 0xbfb8aa3b, v0
	v_lshlrev_b32_e32 v180, 16, v167
	v_and_b32_e32 v181, 0xffff0000, v167
	v_exp_f32_e32 v167, v0
	v_add_f32_e32 v0, 1.0, v161
	v_med3_f32 v161, v176, s73, v159
	v_mul_f32_e32 v161, 0xbfb8aa3b, v161
	v_exp_f32_e32 v161, v161
	v_lshlrev_b32_e32 v186, 16, v169
	v_and_b32_e32 v187, 0xffff0000, v169
	v_rcp_f32_e32 v169, v0
	v_med3_f32 v0, v180, s73, v159
	v_lshlrev_b32_e32 v174, 16, v166
	v_mul_f32_e32 v0, 0xbfb8aa3b, v0
	v_mov_b32_e32 v166, v174
	v_exp_f32_e32 v174, v0
	v_add_f32_e32 v0, 1.0, v161
	v_med3_f32 v161, v177, s73, v159
	v_mul_f32_e32 v161, 0xbfb8aa3b, v161
	v_exp_f32_e32 v161, v161
	v_rcp_f32_e32 v176, v0
	v_med3_f32 v0, v181, s73, v159
	v_mul_f32_e32 v0, 0xbfb8aa3b, v0
	v_exp_f32_e32 v175, v0
	v_add_f32_e32 v0, 1.0, v161
	v_med3_f32 v161, v178, s73, v159
	v_mul_f32_e32 v161, 0xbfb8aa3b, v161
	v_exp_f32_e32 v161, v161
	v_rcp_f32_e32 v177, v0
	v_med3_f32 v0, v184, s73, v159
	v_mul_f32_e32 v0, 0xbfb8aa3b, v0
	v_exp_f32_e32 v178, v0
	v_add_f32_e32 v0, 1.0, v161
	v_med3_f32 v161, v179, s73, v159
	v_mul_f32_e32 v161, 0xbfb8aa3b, v161
	v_exp_f32_e32 v161, v161
	v_rcp_f32_e32 v180, v0
	v_med3_f32 v0, v185, s73, v159
	v_mul_f32_e32 v0, 0xbfb8aa3b, v0
	v_exp_f32_e32 v179, v0
	v_add_f32_e32 v0, 1.0, v161
	v_med3_f32 v161, v182, s73, v159
	v_mul_f32_e32 v161, 0xbfb8aa3b, v161
	v_exp_f32_e32 v161, v161
	v_rcp_f32_e32 v181, v0
	v_med3_f32 v0, v186, s73, v159
	v_mul_f32_e32 v0, 0xbfb8aa3b, v0
	v_exp_f32_e32 v182, v0
	v_add_f32_e32 v0, 1.0, v161
	v_med3_f32 v161, v183, s73, v159
	v_mul_f32_e32 v161, 0xbfb8aa3b, v161
	v_exp_f32_e32 v161, v161
	v_rcp_f32_e32 v184, v0
	v_med3_f32 v0, v187, s73, v159
	v_med3_f32 v166, v166, s73, v159
	v_mul_f32_e32 v0, 0xbfb8aa3b, v0
	v_mul_f32_e32 v166, 0xbfb8aa3b, v166
	v_exp_f32_e32 v183, v0
	v_add_f32_e32 v0, 1.0, v161
	v_exp_f32_e32 v166, v166
	v_rcp_f32_e32 v185, v0
	s_waitcnt vmcnt(1)
	v_lshlrev_b32_e32 v0, 16, v170
	v_med3_f32 v0, v0, s73, v159
	v_mul_f32_e32 v0, 0xbfb8aa3b, v0
	v_pk_add_f32 v[174:175], v[174:175], 1.0 op_sel_hi:[1,0]
	v_pk_add_f32 v[166:167], v[166:167], 1.0 op_sel_hi:[1,0]
	v_and_b32_e32 v161, 0xffff0000, v170
	v_exp_f32_e32 v0, v0
	v_pk_mul_f32 v[166:167], v[166:167], v[168:169]
	v_pk_mul_f32 v[168:169], v[174:175], v[176:177]
	v_pk_mul_f32 v[82:83], v[82:83], v[168:169]
	v_pk_add_f32 v[168:169], v[178:179], 1.0 op_sel_hi:[1,0]
	v_med3_f32 v161, v161, s73, v159
	v_pk_mul_f32 v[168:169], v[168:169], v[180:181]
	v_mul_f32_e32 v161, 0xbfb8aa3b, v161
	v_pk_mul_f32 v[76:77], v[76:77], v[168:169]
	s_waitcnt vmcnt(0)
	v_and_b32_e32 v169, 0xffff0000, v162
	v_add_f32_e32 v0, 1.0, v0
	v_exp_f32_e32 v161, v161
	v_pk_mul_f32 v[80:81], v[80:81], v[166:167]
	v_pk_add_f32 v[166:167], v[182:183], 1.0 op_sel_hi:[1,0]
	v_lshlrev_b32_e32 v176, 16, v164
	v_and_b32_e32 v177, 0xffff0000, v164
	v_rcp_f32_e32 v164, v0
	v_pk_mul_f32 v[166:167], v[166:167], v[184:185]
	v_med3_f32 v0, v169, s73, v159
	v_pk_mul_f32 v[78:79], v[78:79], v[166:167]
	v_lshlrev_b32_e32 v166, 16, v171
	v_mul_f32_e32 v0, 0xbfb8aa3b, v0
	v_and_b32_e32 v167, 0xffff0000, v171
	v_lshlrev_b32_e32 v170, 16, v172
	v_and_b32_e32 v171, 0xffff0000, v172
	v_lshlrev_b32_e32 v174, 16, v173
	v_and_b32_e32 v175, 0xffff0000, v173
	v_lshlrev_b32_e32 v172, 16, v163
	v_and_b32_e32 v173, 0xffff0000, v163
	v_exp_f32_e32 v163, v0
	v_add_f32_e32 v0, 1.0, v161
	v_med3_f32 v161, v166, s73, v159
	v_mul_f32_e32 v161, 0xbfb8aa3b, v161
	v_exp_f32_e32 v161, v161
	v_lshlrev_b32_e32 v178, 16, v165
	v_and_b32_e32 v179, 0xffff0000, v165
	v_rcp_f32_e32 v165, v0
	v_med3_f32 v0, v172, s73, v159
	v_mul_f32_e32 v0, 0xbfb8aa3b, v0
	v_exp_f32_e32 v166, v0
	v_add_f32_e32 v0, 1.0, v161
	v_med3_f32 v161, v167, s73, v159
	v_mul_f32_e32 v161, 0xbfb8aa3b, v161
	v_lshlrev_b32_e32 v168, 16, v162
	v_exp_f32_e32 v161, v161
	v_mov_b32_e32 v162, v168
	v_rcp_f32_e32 v168, v0
	v_med3_f32 v0, v173, s73, v159
	v_mul_f32_e32 v0, 0xbfb8aa3b, v0
	v_exp_f32_e32 v167, v0
	v_add_f32_e32 v0, 1.0, v161
	v_med3_f32 v161, v170, s73, v159
	v_mul_f32_e32 v161, 0xbfb8aa3b, v161
	v_exp_f32_e32 v161, v161
	v_rcp_f32_e32 v169, v0
	v_med3_f32 v0, v176, s73, v159
	v_mul_f32_e32 v0, 0xbfb8aa3b, v0
	v_exp_f32_e32 v170, v0
	v_add_f32_e32 v0, 1.0, v161
	v_med3_f32 v161, v171, s73, v159
	v_mul_f32_e32 v161, 0xbfb8aa3b, v161
	v_exp_f32_e32 v161, v161
	v_rcp_f32_e32 v172, v0
	v_med3_f32 v0, v177, s73, v159
	v_mul_f32_e32 v0, 0xbfb8aa3b, v0
	v_exp_f32_e32 v171, v0
	v_add_f32_e32 v0, 1.0, v161
	v_med3_f32 v161, v174, s73, v159
	v_mul_f32_e32 v161, 0xbfb8aa3b, v161
	v_exp_f32_e32 v161, v161
	v_rcp_f32_e32 v173, v0
	v_med3_f32 v0, v178, s73, v159
	v_mul_f32_e32 v0, 0xbfb8aa3b, v0
	v_exp_f32_e32 v174, v0
	v_add_f32_e32 v0, 1.0, v161
	v_med3_f32 v161, v175, s73, v159
	v_mul_f32_e32 v161, 0xbfb8aa3b, v161
	v_med3_f32 v162, v162, s73, v159
	v_exp_f32_e32 v161, v161
	v_mul_f32_e32 v162, 0xbfb8aa3b, v162
	v_rcp_f32_e32 v176, v0
	v_exp_f32_e32 v162, v162
	v_med3_f32 v0, v179, s73, v159
	v_mul_f32_e32 v0, 0xbfb8aa3b, v0
	v_exp_f32_e32 v175, v0
	v_add_f32_e32 v0, 1.0, v161
	v_rcp_f32_e32 v177, v0
	v_pk_add_f32 v[166:167], v[166:167], 1.0 op_sel_hi:[1,0]
	v_pk_add_f32 v[162:163], v[162:163], 1.0 op_sel_hi:[1,0]
	s_nop 0
	v_pk_mul_f32 v[162:163], v[162:163], v[164:165]
	v_pk_mul_f32 v[164:165], v[166:167], v[168:169]
	v_pk_mul_f32 v[72:73], v[72:73], v[162:163]
	v_pk_mul_f32 v[74:75], v[74:75], v[164:165]
	v_pk_add_f32 v[162:163], v[174:175], 1.0 op_sel_hi:[1,0]
	v_pk_add_f32 v[164:165], v[170:171], 1.0 op_sel_hi:[1,0]
	v_pk_mul_f32 v[162:163], v[162:163], v[176:177]
	v_pk_mul_f32 v[164:165], v[164:165], v[172:173]
	v_pk_mul_f32 v[70:71], v[70:71], v[162:163]
	v_pk_mul_f32 v[68:69], v[68:69], v[164:165]
	v_add_co_u32_e32 v162, vcc, s77, v2
	v_lshl_add_u64 v[170:171], v[2:3], 0, s[18:19]
	s_nop 0
	v_addc_co_u32_e32 v163, vcc, 0, v3, vcc
	v_add_co_u32_e32 v174, vcc, s78, v2
	global_load_dwordx4 v[162:165], v[162:163], off
	s_nop 0
	v_addc_co_u32_e32 v175, vcc, 0, v3, vcc
	global_load_dwordx4 v[166:169], v[174:175], off
	s_nop 0
	global_load_dwordx4 v[170:173], v[170:171], off offset:256
	s_nop 0
	global_load_dwordx4 v[174:177], v[174:175], off offset:256
	s_waitcnt vmcnt(3)
; __device__ __forceinline__ float bflo(unsigned w) { return __uint_as_float(w << 16); }
; __device__ __forceinline__ float bfhi(unsigned w) { return __uint_as_float(w & 0xffff0000u); }
;     static __device__ __forceinline__ float cl(float x) { return fminf(fmaxf(x, -30.f), 30.f); }
;     __device__ __forceinline__ void mid(f32x4 (&acc)[2][2][4][2], const Unit& u, int wr, int wc, int fr, int fq) const {
;     ...
;             for (int m = 0; m < 4; ++m) { const size_t row = (size_t)(row0 + ai * HALF + m * 16);
; #pragma unroll
;                 for (int bj = 0; bj < 2; ++bj) { const int col = u.pn * BM + bj * HALF + wc * 32 + 8 * fq;
;                     const bf16_t* gp = gate + (size_t)(col >> 10) * SEC + row * 1024 + (col & 1023);
;                     const u32x4 ga = *(const u32x4*)gp, gb = *(const u32x4*)(gp + 2 * SEC);
;                     float ea[8] = {bflo(ga.x), bfhi(ga.x), bflo(ga.y), bfhi(ga.y), bflo(ga.z), bfhi(ga.z), bflo(ga.w), bfhi(ga.w)};
;                     float eb[8] = {bflo(gb.x), bfhi(gb.x), bflo(gb.y), bfhi(gb.y), bflo(gb.z), bfhi(gb.z), bflo(gb.w), bfhi(gb.w)};
;                     float r[8];
; #pragma unroll
;                     for (int e = 0; e < 8; ++e) r[e] = (1.f + __expf(-cl(eb[e]))) * __builtin_amdgcn_rcpf(1.f + __expf(-cl(ea[e])));
;                     acc[ai][bj][m][0][0] *= r[0]; acc[ai][bj][m][0][1] *= r[1]; acc[ai][bj][m][0][2] *= r[2]; acc[ai][bj][m][0][3] *= r[3];
;                     acc[ai][bj][m][1][0] *= r[4]; acc[ai][bj][m][1][1] *= r[5]; acc[ai][bj][m][1][2] *= r[6]; acc[ai][bj][m][1][3] *= r[7]; }
	v_lshlrev_b32_e32 v0, 16, v162
	v_and_b32_e32 v161, 0xffff0000, v162
	v_lshlrev_b32_e32 v178, 16, v164
	v_and_b32_e32 v164, 0xffff0000, v164
	v_lshlrev_b32_e32 v179, 16, v165
	v_and_b32_e32 v183, 0xffff0000, v165
	s_waitcnt vmcnt(2)
	v_lshlrev_b32_e32 v165, 16, v166
	v_lshlrev_b32_e32 v180, 16, v167
	v_and_b32_e32 v167, 0xffff0000, v167
	v_lshlrev_b32_e32 v181, 16, v168
	v_and_b32_e32 v168, 0xffff0000, v168
	v_lshlrev_b32_e32 v162, 16, v163
	v_med3_f32 v0, v0, s73, v159
	v_lshlrev_b32_e32 v182, 16, v169
	v_and_b32_e32 v185, 0xffff0000, v169
	v_med3_f32 v165, v165, s73, v159
	v_med3_f32 v161, v161, s73, v159
	v_med3_f32 v167, v167, s73, v159
	v_med3_f32 v168, v168, s73, v159
	v_med3_f32 v164, v164, s73, v159
	v_mul_f32_e32 v0, 0xbfb8aa3b, v0
	v_med3_f32 v169, v180, s73, v159
	v_med3_f32 v162, v162, s73, v159
	v_mul_f32_e32 v165, 0xbfb8aa3b, v165
	v_mul_f32_e32 v161, 0xbfb8aa3b, v161
	v_mul_f32_e32 v167, 0xbfb8aa3b, v167
	v_mul_f32_e32 v168, 0xbfb8aa3b, v168
	v_mul_f32_e32 v186, 0xbfb8aa3b, v164
	v_exp_f32_e32 v0, v0
	v_mov_b32_e32 v184, v179
	v_med3_f32 v179, v181, s73, v159
	v_mul_f32_e32 v169, 0xbfb8aa3b, v169
	v_mul_f32_e32 v180, 0xbfb8aa3b, v162
	v_exp_f32_e32 v162, v165
	v_exp_f32_e32 v161, v161
	v_exp_f32_e32 v165, v167
	v_exp_f32_e32 v167, v168
	v_exp_f32_e32 v168, v186
	v_and_b32_e32 v166, 0xffff0000, v166
	v_exp_f32_e32 v164, v169
	v_exp_f32_e32 v169, v180
	v_and_b32_e32 v163, 0xffff0000, v163
	v_med3_f32 v166, v166, s73, v159
	v_add_f32_e32 v0, 1.0, v0
	v_med3_f32 v163, v163, s73, v159
	v_mul_f32_e32 v166, 0xbfb8aa3b, v166
	v_mul_f32_e32 v179, 0xbfb8aa3b, v179
	v_add_f32_e32 v161, 1.0, v161
	v_add_f32_e32 v186, 1.0, v168
	v_rcp_f32_e32 v168, v0
	v_med3_f32 v0, v184, s73, v159
	v_mul_f32_e32 v181, 0xbfb8aa3b, v163
	v_exp_f32_e32 v163, v166
	v_exp_f32_e32 v166, v179
	v_add_f32_e32 v179, 1.0, v169
	v_rcp_f32_e32 v169, v161
	v_mul_f32_e32 v0, 0xbfb8aa3b, v0
	v_med3_f32 v161, v182, s73, v159
	v_exp_f32_e32 v0, v0
	v_mul_f32_e32 v161, 0xbfb8aa3b, v161
	v_exp_f32_e32 v182, v161
	v_med3_f32 v161, v183, s73, v159
	v_mul_f32_e32 v161, 0xbfb8aa3b, v161
	v_add_f32_e32 v0, 1.0, v0
	v_exp_f32_e32 v161, v161
	v_rcp_f32_e32 v184, v0
	v_med3_f32 v0, v185, s73, v159
	v_med3_f32 v178, v178, s73, v159
	v_mul_f32_e32 v0, 0xbfb8aa3b, v0
	v_mul_f32_e32 v178, 0xbfb8aa3b, v178
	v_exp_f32_e32 v180, v181
	v_exp_f32_e32 v183, v0
	v_add_f32_e32 v0, 1.0, v161
	v_exp_f32_e32 v178, v178
	v_rcp_f32_e32 v185, v0
	v_pk_add_f32 v[162:163], v[162:163], 1.0 op_sel_hi:[1,0]
	s_waitcnt vmcnt(1)
	v_lshlrev_b32_e32 v0, 16, v170
	v_pk_mul_f32 v[162:163], v[162:163], v[168:169]
	v_add_f32_e32 v180, 1.0, v180
	v_pk_mul_f32 v[64:65], v[64:65], v[162:163]
	v_pk_add_f32 v[162:163], v[182:183], 1.0 op_sel_hi:[1,0]
	v_med3_f32 v0, v0, s73, v159
	v_add_f32_e32 v181, 1.0, v178
	v_rcp_f32_e32 v178, v179
	v_rcp_f32_e32 v179, v180
	v_pk_mul_f32 v[162:163], v[162:163], v[184:185]
	v_mul_f32_e32 v0, 0xbfb8aa3b, v0
	v_pk_mul_f32 v[62:63], v[62:63], v[162:163]
	s_waitcnt vmcnt(0)
	v_lshlrev_b32_e32 v162, 16, v174
	v_exp_f32_e32 v0, v0
	v_rcp_f32_e32 v180, v181
	v_rcp_f32_e32 v181, v186
	v_pk_add_f32 v[164:165], v[164:165], 1.0 op_sel_hi:[1,0]
	v_med3_f32 v162, v162, s73, v159
	v_pk_mul_f32 v[164:165], v[164:165], v[178:179]
	v_mul_f32_e32 v162, 0xbfb8aa3b, v162
	v_pk_mul_f32 v[66:67], v[66:67], v[164:165]
	v_pk_add_f32 v[164:165], v[166:167], 1.0 op_sel_hi:[1,0]
	v_and_b32_e32 v161, 0xffff0000, v170
	v_and_b32_e32 v163, 0xffff0000, v174
	v_exp_f32_e32 v170, v162
	v_add_f32_e32 v0, 1.0, v0
	v_add_co_u32_e32 v162, vcc, s79, v2
	v_pk_mul_f32 v[164:165], v[164:165], v[180:181]
	v_lshlrev_b32_e32 v180, 16, v172
	v_and_b32_e32 v181, 0xffff0000, v172
	v_rcp_f32_e32 v172, v0
	v_mov_b32_e32 v0, v163
	v_addc_co_u32_e32 v163, vcc, 0, v3, vcc
	v_pk_mul_f32 v[60:61], v[60:61], v[164:165]
	global_load_dwordx4 v[162:165], v[162:163], off
	v_med3_f32 v161, v161, s73, v159
	v_mul_f32_e32 v161, 0xbfb8aa3b, v161
	v_exp_f32_e32 v161, v161
	v_med3_f32 v0, v0, s73, v159
	v_lshlrev_b32_e32 v166, 16, v171
	v_mul_f32_e32 v0, 0xbfb8aa3b, v0
	v_and_b32_e32 v179, 0xffff0000, v171
	v_exp_f32_e32 v171, v0
	v_add_f32_e32 v0, 1.0, v161
	v_add_co_u32_e32 v174, vcc, s80, v2
	v_lshlrev_b32_e32 v167, 16, v175
	v_and_b32_e32 v182, 0xffff0000, v175
	v_med3_f32 v161, v166, s73, v159
	v_addc_co_u32_e32 v175, vcc, 0, v3, vcc
	v_lshlrev_b32_e32 v184, 16, v173
	v_and_b32_e32 v185, 0xffff0000, v173
	v_rcp_f32_e32 v173, v0
	v_mov_b32_e32 v0, v167
	v_mul_f32_e32 v161, 0xbfb8aa3b, v161
	global_load_dwordx4 v[166:169], v[174:175], off
	v_exp_f32_e32 v161, v161
	v_med3_f32 v0, v0, s73, v159
	v_mul_f32_e32 v0, 0xbfb8aa3b, v0
	v_lshlrev_b32_e32 v183, 16, v176
	v_and_b32_e32 v186, 0xffff0000, v176
	v_exp_f32_e32 v176, v0
	v_add_f32_e32 v0, 1.0, v161
	v_med3_f32 v161, v179, s73, v159
	v_mul_f32_e32 v161, 0xbfb8aa3b, v161
	v_exp_f32_e32 v161, v161
	v_rcp_f32_e32 v178, v0
	v_med3_f32 v0, v182, s73, v159
	v_mul_f32_e32 v0, 0xbfb8aa3b, v0
	v_lshlrev_b32_e32 v187, 16, v177
	v_and_b32_e32 v188, 0xffff0000, v177
	v_exp_f32_e32 v177, v0
	v_add_f32_e32 v0, 1.0, v161
	v_med3_f32 v161, v180, s73, v159
	v_mul_f32_e32 v161, 0xbfb8aa3b, v161
	v_exp_f32_e32 v161, v161
	v_rcp_f32_e32 v179, v0
	v_med3_f32 v0, v183, s73, v159
	v_mul_f32_e32 v0, 0xbfb8aa3b, v0
	v_exp_f32_e32 v180, v0
	v_add_f32_e32 v0, 1.0, v161
	v_med3_f32 v161, v181, s73, v159
	v_mul_f32_e32 v161, 0xbfb8aa3b, v161
	v_exp_f32_e32 v161, v161
	v_rcp_f32_e32 v182, v0
	v_med3_f32 v0, v186, s73, v159
	v_mul_f32_e32 v0, 0xbfb8aa3b, v0
	v_exp_f32_e32 v181, v0
	v_add_f32_e32 v0, 1.0, v161
	v_med3_f32 v161, v184, s73, v159
	v_mul_f32_e32 v161, 0xbfb8aa3b, v161
	v_exp_f32_e32 v161, v161
	v_rcp_f32_e32 v183, v0
	v_med3_f32 v0, v187, s73, v159
	v_mul_f32_e32 v0, 0xbfb8aa3b, v0
	v_exp_f32_e32 v184, v0
	v_add_f32_e32 v0, 1.0, v161
	v_med3_f32 v161, v185, s73, v159
	v_mul_f32_e32 v161, 0xbfb8aa3b, v161
	v_exp_f32_e32 v161, v161
	v_rcp_f32_e32 v186, v0
	v_med3_f32 v0, v188, s73, v159
	v_mul_f32_e32 v0, 0xbfb8aa3b, v0
	v_exp_f32_e32 v185, v0
	v_add_f32_e32 v0, 1.0, v161
	v_rcp_f32_e32 v187, v0
	v_pk_add_f32 v[170:171], v[170:171], 1.0 op_sel_hi:[1,0]
	v_pk_add_f32 v[176:177], v[176:177], 1.0 op_sel_hi:[1,0]
	v_pk_mul_f32 v[170:171], v[170:171], v[172:173]
	v_pk_mul_f32 v[172:173], v[176:177], v[178:179]
	v_pk_mul_f32 v[56:57], v[56:57], v[170:171]
	v_pk_add_f32 v[170:171], v[184:185], 1.0 op_sel_hi:[1,0]
	v_pk_mul_f32 v[58:59], v[58:59], v[172:173]
	v_pk_add_f32 v[172:173], v[180:181], 1.0 op_sel_hi:[1,0]
	v_pk_mul_f32 v[170:171], v[170:171], v[186:187]
	v_pk_mul_f32 v[172:173], v[172:173], v[182:183]
	v_pk_mul_f32 v[54:55], v[54:55], v[170:171]
	v_lshl_add_u64 v[170:171], v[2:3], 0, s[20:21]
	v_pk_mul_f32 v[52:53], v[52:53], v[172:173]
	global_load_dwordx4 v[170:173], v[170:171], off offset:256
	s_waitcnt vmcnt(2)
; __device__ __forceinline__ float bflo(unsigned w) { return __uint_as_float(w << 16); }
; __device__ __forceinline__ float bfhi(unsigned w) { return __uint_as_float(w & 0xffff0000u); }
;     static __device__ __forceinline__ float cl(float x) { return fminf(fmaxf(x, -30.f), 30.f); }
;     __device__ __forceinline__ void mid(f32x4 (&acc)[2][2][4][2], const Unit& u, int wr, int wc, int fr, int fq) const {
;     ...
;             for (int m = 0; m < 4; ++m) { const size_t row = (size_t)(row0 + ai * HALF + m * 16);
; #pragma unroll
;                 for (int bj = 0; bj < 2; ++bj) { const int col = u.pn * BM + bj * HALF + wc * 32 + 8 * fq;
;                     const bf16_t* gp = gate + (size_t)(col >> 10) * SEC + row * 1024 + (col & 1023);
;                     const u32x4 ga = *(const u32x4*)gp, gb = *(const u32x4*)(gp + 2 * SEC);
;                     float ea[8] = {bflo(ga.x), bfhi(ga.x), bflo(ga.y), bfhi(ga.y), bflo(ga.z), bfhi(ga.z), bflo(ga.w), bfhi(ga.w)};
;                     float eb[8] = {bflo(gb.x), bfhi(gb.x), bflo(gb.y), bfhi(gb.y), bflo(gb.z), bfhi(gb.z), bflo(gb.w), bfhi(gb.w)};
;                     float r[8];
; #pragma unroll
;                     for (int e = 0; e < 8; ++e) r[e] = (1.f + __expf(-cl(eb[e]))) * __builtin_amdgcn_rcpf(1.f + __expf(-cl(ea[e])));
;                     acc[ai][bj][m][0][0] *= r[0]; acc[ai][bj][m][0][1] *= r[1]; acc[ai][bj][m][0][2] *= r[2]; acc[ai][bj][m][0][3] *= r[3];
;                     acc[ai][bj][m][1][0] *= r[4]; acc[ai][bj][m][1][1] *= r[5]; acc[ai][bj][m][1][2] *= r[6]; acc[ai][bj][m][1][3] *= r[7]; }
	v_lshlrev_b32_e32 v0, 16, v162
	v_and_b32_e32 v161, 0xffff0000, v162
	v_lshlrev_b32_e32 v176, 16, v163
	v_and_b32_e32 v177, 0xffff0000, v163
	v_lshlrev_b32_e32 v178, 16, v164
	v_and_b32_e32 v179, 0xffff0000, v164
	v_lshlrev_b32_e32 v182, 16, v165
	v_and_b32_e32 v183, 0xffff0000, v165
	global_load_dwordx4 v[162:165], v[174:175], off offset:256
	v_med3_f32 v0, v0, s73, v159
	v_mul_f32_e32 v0, 0xbfb8aa3b, v0
	v_exp_f32_e32 v0, v0
	v_med3_f32 v161, v161, s73, v159
	v_mul_f32_e32 v161, 0xbfb8aa3b, v161
	s_waitcnt vmcnt(2)
	v_and_b32_e32 v175, 0xffff0000, v166
	v_add_f32_e32 v0, 1.0, v0
	v_exp_f32_e32 v161, v161
	v_lshlrev_b32_e32 v184, 16, v168
	v_and_b32_e32 v185, 0xffff0000, v168
	v_rcp_f32_e32 v168, v0
	v_med3_f32 v0, v175, s73, v159
	v_mul_f32_e32 v0, 0xbfb8aa3b, v0
	v_lshlrev_b32_e32 v180, 16, v167
	v_and_b32_e32 v181, 0xffff0000, v167
	v_exp_f32_e32 v167, v0
	v_add_f32_e32 v0, 1.0, v161
	v_med3_f32 v161, v176, s73, v159
	v_mul_f32_e32 v161, 0xbfb8aa3b, v161
	v_exp_f32_e32 v161, v161
	v_lshlrev_b32_e32 v186, 16, v169
	v_and_b32_e32 v187, 0xffff0000, v169
	v_rcp_f32_e32 v169, v0
	v_med3_f32 v0, v180, s73, v159
	v_lshlrev_b32_e32 v174, 16, v166
	v_mul_f32_e32 v0, 0xbfb8aa3b, v0
	v_mov_b32_e32 v166, v174
	v_exp_f32_e32 v174, v0
	v_add_f32_e32 v0, 1.0, v161
	v_med3_f32 v161, v177, s73, v159
	v_mul_f32_e32 v161, 0xbfb8aa3b, v161
	v_exp_f32_e32 v161, v161
	v_rcp_f32_e32 v176, v0
	v_med3_f32 v0, v181, s73, v159
	v_mul_f32_e32 v0, 0xbfb8aa3b, v0
	v_exp_f32_e32 v175, v0
	v_add_f32_e32 v0, 1.0, v161
	v_med3_f32 v161, v178, s73, v159
	v_mul_f32_e32 v161, 0xbfb8aa3b, v161
	v_exp_f32_e32 v161, v161
	v_rcp_f32_e32 v177, v0
	v_med3_f32 v0, v184, s73, v159
	v_mul_f32_e32 v0, 0xbfb8aa3b, v0
	v_exp_f32_e32 v178, v0
	v_add_f32_e32 v0, 1.0, v161
	v_med3_f32 v161, v179, s73, v159
	v_mul_f32_e32 v161, 0xbfb8aa3b, v161
	v_exp_f32_e32 v161, v161
	v_rcp_f32_e32 v180, v0
	v_med3_f32 v0, v185, s73, v159
	v_mul_f32_e32 v0, 0xbfb8aa3b, v0
	v_exp_f32_e32 v179, v0
	v_add_f32_e32 v0, 1.0, v161
	v_med3_f32 v161, v182, s73, v159
	v_mul_f32_e32 v161, 0xbfb8aa3b, v161
	v_exp_f32_e32 v161, v161
	v_rcp_f32_e32 v181, v0
	v_med3_f32 v0, v186, s73, v159
	v_mul_f32_e32 v0, 0xbfb8aa3b, v0
	v_exp_f32_e32 v182, v0
	v_add_f32_e32 v0, 1.0, v161
	v_med3_f32 v161, v183, s73, v159
	v_mul_f32_e32 v161, 0xbfb8aa3b, v161
	v_exp_f32_e32 v161, v161
	v_med3_f32 v166, v166, s73, v159
	v_rcp_f32_e32 v184, v0
	v_mul_f32_e32 v166, 0xbfb8aa3b, v166
	v_med3_f32 v0, v187, s73, v159
	v_exp_f32_e32 v166, v166
	v_mul_f32_e32 v0, 0xbfb8aa3b, v0
	v_exp_f32_e32 v183, v0
	v_add_f32_e32 v0, 1.0, v161
	v_rcp_f32_e32 v185, v0
	s_waitcnt vmcnt(1)
	v_lshlrev_b32_e32 v0, 16, v170
	v_pk_add_f32 v[166:167], v[166:167], 1.0 op_sel_hi:[1,0]
	v_med3_f32 v0, v0, s73, v159
	v_pk_add_f32 v[174:175], v[174:175], 1.0 op_sel_hi:[1,0]
	v_pk_mul_f32 v[166:167], v[166:167], v[168:169]
	v_mul_f32_e32 v0, 0xbfb8aa3b, v0
	v_pk_mul_f32 v[168:169], v[174:175], v[176:177]
	v_pk_mul_f32 v[48:49], v[48:49], v[166:167]
	v_pk_add_f32 v[166:167], v[182:183], 1.0 op_sel_hi:[1,0]
	v_exp_f32_e32 v0, v0
	v_pk_mul_f32 v[50:51], v[50:51], v[168:169]
	v_pk_add_f32 v[168:169], v[178:179], 1.0 op_sel_hi:[1,0]
	v_pk_mul_f32 v[166:167], v[166:167], v[184:185]
	v_pk_mul_f32 v[168:169], v[168:169], v[180:181]
	v_pk_mul_f32 v[46:47], v[46:47], v[166:167]
	s_waitcnt vmcnt(0)
	v_lshlrev_b32_e32 v167, 16, v162
	v_pk_mul_f32 v[44:45], v[44:45], v[168:169]
	v_lshlrev_b32_e32 v168, 16, v163
	v_and_b32_e32 v179, 0xffff0000, v163
	v_and_b32_e32 v162, 0xffff0000, v162
	v_med3_f32 v163, v167, s73, v159
	v_add_f32_e32 v0, 1.0, v0
	v_lshlrev_b32_e32 v180, 16, v172
	v_and_b32_e32 v181, 0xffff0000, v172
	v_mul_f32_e32 v163, 0xbfb8aa3b, v163
	v_rcp_f32_e32 v172, v0
	v_mov_b32_e32 v0, v162
	v_add_co_u32_e32 v162, vcc, s81, v2
	v_and_b32_e32 v161, 0xffff0000, v170
	v_exp_f32_e32 v170, v163
	v_addc_co_u32_e32 v163, vcc, 0, v3, vcc
	v_lshlrev_b32_e32 v182, 16, v164
	v_and_b32_e32 v183, 0xffff0000, v164
	v_lshlrev_b32_e32 v186, 16, v165
	v_and_b32_e32 v187, 0xffff0000, v165
	global_load_dwordx4 v[162:165], v[162:163], off
	v_med3_f32 v161, v161, s73, v159
	v_mul_f32_e32 v161, 0xbfb8aa3b, v161
	v_exp_f32_e32 v161, v161
	v_med3_f32 v0, v0, s73, v159
	v_lshlrev_b32_e32 v166, 16, v171
	v_mul_f32_e32 v0, 0xbfb8aa3b, v0
	v_and_b32_e32 v177, 0xffff0000, v171
	v_exp_f32_e32 v171, v0
	v_add_f32_e32 v0, 1.0, v161
	v_add_co_u32_e32 v174, vcc, s82, v2
	v_med3_f32 v161, v166, s73, v159
	s_nop 0
	v_addc_co_u32_e32 v175, vcc, 0, v3, vcc
	v_lshlrev_b32_e32 v184, 16, v173
	v_and_b32_e32 v185, 0xffff0000, v173
	v_rcp_f32_e32 v173, v0
	v_mov_b32_e32 v0, v168
	v_mul_f32_e32 v161, 0xbfb8aa3b, v161
	global_load_dwordx4 v[166:169], v[174:175], off
	v_exp_f32_e32 v161, v161
	v_med3_f32 v0, v0, s73, v159
	v_mul_f32_e32 v0, 0xbfb8aa3b, v0
	v_exp_f32_e32 v176, v0
	v_add_f32_e32 v0, 1.0, v161
	v_med3_f32 v161, v177, s73, v159
	v_mul_f32_e32 v161, 0xbfb8aa3b, v161
	v_exp_f32_e32 v161, v161
	v_rcp_f32_e32 v178, v0
	v_med3_f32 v0, v179, s73, v159
	v_mul_f32_e32 v0, 0xbfb8aa3b, v0
	v_exp_f32_e32 v177, v0
	v_add_f32_e32 v0, 1.0, v161
	v_med3_f32 v161, v180, s73, v159
	v_mul_f32_e32 v161, 0xbfb8aa3b, v161
	v_exp_f32_e32 v161, v161
	v_rcp_f32_e32 v179, v0
	v_med3_f32 v0, v182, s73, v159
	v_mul_f32_e32 v0, 0xbfb8aa3b, v0
	v_exp_f32_e32 v180, v0
	v_add_f32_e32 v0, 1.0, v161
	v_med3_f32 v161, v181, s73, v159
	v_mul_f32_e32 v161, 0xbfb8aa3b, v161
	v_exp_f32_e32 v161, v161
	v_rcp_f32_e32 v182, v0
	v_med3_f32 v0, v183, s73, v159
	v_mul_f32_e32 v0, 0xbfb8aa3b, v0
	v_exp_f32_e32 v181, v0
	v_add_f32_e32 v0, 1.0, v161
	v_med3_f32 v161, v184, s73, v159
	v_mul_f32_e32 v161, 0xbfb8aa3b, v161
	v_exp_f32_e32 v161, v161
	v_rcp_f32_e32 v183, v0
	v_med3_f32 v0, v186, s73, v159
	v_mul_f32_e32 v0, 0xbfb8aa3b, v0
	v_exp_f32_e32 v184, v0
	v_add_f32_e32 v0, 1.0, v161
	v_med3_f32 v161, v185, s73, v159
	v_mul_f32_e32 v161, 0xbfb8aa3b, v161
	v_exp_f32_e32 v161, v161
	v_rcp_f32_e32 v186, v0
	v_med3_f32 v0, v187, s73, v159
	v_mul_f32_e32 v0, 0xbfb8aa3b, v0
	v_exp_f32_e32 v185, v0
	v_add_f32_e32 v0, 1.0, v161
	v_rcp_f32_e32 v187, v0
	v_pk_add_f32 v[170:171], v[170:171], 1.0 op_sel_hi:[1,0]
	v_pk_add_f32 v[176:177], v[176:177], 1.0 op_sel_hi:[1,0]
	v_pk_mul_f32 v[170:171], v[170:171], v[172:173]
	v_pk_mul_f32 v[172:173], v[176:177], v[178:179]
	v_pk_mul_f32 v[40:41], v[40:41], v[170:171]
	v_pk_add_f32 v[170:171], v[184:185], 1.0 op_sel_hi:[1,0]
	v_pk_mul_f32 v[42:43], v[42:43], v[172:173]
	v_pk_add_f32 v[172:173], v[180:181], 1.0 op_sel_hi:[1,0]
	v_pk_mul_f32 v[170:171], v[170:171], v[186:187]
	v_pk_mul_f32 v[172:173], v[172:173], v[182:183]
	v_pk_mul_f32 v[38:39], v[38:39], v[170:171]
	v_lshl_add_u64 v[170:171], v[2:3], 0, s[22:23]
	v_pk_mul_f32 v[36:37], v[36:37], v[172:173]
	global_load_dwordx4 v[170:173], v[170:171], off offset:256
	s_waitcnt vmcnt(2)
; __device__ __forceinline__ float bflo(unsigned w) { return __uint_as_float(w << 16); }
; __device__ __forceinline__ float bfhi(unsigned w) { return __uint_as_float(w & 0xffff0000u); }
;     static __device__ __forceinline__ float cl(float x) { return fminf(fmaxf(x, -30.f), 30.f); }
;     __device__ __forceinline__ void mid(f32x4 (&acc)[2][2][4][2], const Unit& u, int wr, int wc, int fr, int fq) const {
;     ...
;             for (int m = 0; m < 4; ++m) { const size_t row = (size_t)(row0 + ai * HALF + m * 16);
; #pragma unroll
;                 for (int bj = 0; bj < 2; ++bj) { const int col = u.pn * BM + bj * HALF + wc * 32 + 8 * fq;
;                     const bf16_t* gp = gate + (size_t)(col >> 10) * SEC + row * 1024 + (col & 1023);
;                     const u32x4 ga = *(const u32x4*)gp, gb = *(const u32x4*)(gp + 2 * SEC);
;                     float ea[8] = {bflo(ga.x), bfhi(ga.x), bflo(ga.y), bfhi(ga.y), bflo(ga.z), bfhi(ga.z), bflo(ga.w), bfhi(ga.w)};
;                     float eb[8] = {bflo(gb.x), bfhi(gb.x), bflo(gb.y), bfhi(gb.y), bflo(gb.z), bfhi(gb.z), bflo(gb.w), bfhi(gb.w)};
;                     float r[8];
; #pragma unroll
;                     for (int e = 0; e < 8; ++e) r[e] = (1.f + __expf(-cl(eb[e]))) * __builtin_amdgcn_rcpf(1.f + __expf(-cl(ea[e])));
;                     acc[ai][bj][m][0][0] *= r[0]; acc[ai][bj][m][0][1] *= r[1]; acc[ai][bj][m][0][2] *= r[2]; acc[ai][bj][m][0][3] *= r[3];
;                     acc[ai][bj][m][1][0] *= r[4]; acc[ai][bj][m][1][1] *= r[5]; acc[ai][bj][m][1][2] *= r[6]; acc[ai][bj][m][1][3] *= r[7]; }
	v_lshlrev_b32_e32 v0, 16, v162
	v_and_b32_e32 v161, 0xffff0000, v162
	v_lshlrev_b32_e32 v176, 16, v163
	v_and_b32_e32 v177, 0xffff0000, v163
	v_lshlrev_b32_e32 v178, 16, v164
	v_and_b32_e32 v179, 0xffff0000, v164
	v_lshlrev_b32_e32 v182, 16, v165
	v_and_b32_e32 v183, 0xffff0000, v165
	global_load_dwordx4 v[162:165], v[174:175], off offset:256
	v_med3_f32 v0, v0, s73, v159
	v_mul_f32_e32 v0, 0xbfb8aa3b, v0
	v_exp_f32_e32 v0, v0
	v_med3_f32 v161, v161, s73, v159
	v_mul_f32_e32 v161, 0xbfb8aa3b, v161
	s_waitcnt vmcnt(2)
	v_and_b32_e32 v175, 0xffff0000, v166
	v_add_f32_e32 v0, 1.0, v0
	v_exp_f32_e32 v161, v161
	v_lshlrev_b32_e32 v184, 16, v168
	v_and_b32_e32 v185, 0xffff0000, v168
	v_rcp_f32_e32 v168, v0
	v_med3_f32 v0, v175, s73, v159
	v_mul_f32_e32 v0, 0xbfb8aa3b, v0
	v_lshlrev_b32_e32 v180, 16, v167
	v_and_b32_e32 v181, 0xffff0000, v167
	v_exp_f32_e32 v167, v0
	v_add_f32_e32 v0, 1.0, v161
	v_med3_f32 v161, v176, s73, v159
	v_mul_f32_e32 v161, 0xbfb8aa3b, v161
	v_exp_f32_e32 v161, v161
	v_lshlrev_b32_e32 v186, 16, v169
	v_and_b32_e32 v187, 0xffff0000, v169
	v_rcp_f32_e32 v169, v0
	v_med3_f32 v0, v180, s73, v159
	v_lshlrev_b32_e32 v174, 16, v166
	v_mul_f32_e32 v0, 0xbfb8aa3b, v0
	v_mov_b32_e32 v166, v174
	v_exp_f32_e32 v174, v0
	v_add_f32_e32 v0, 1.0, v161
	v_med3_f32 v161, v177, s73, v159
	v_mul_f32_e32 v161, 0xbfb8aa3b, v161
	v_exp_f32_e32 v161, v161
	v_rcp_f32_e32 v176, v0
	v_med3_f32 v0, v181, s73, v159
	v_mul_f32_e32 v0, 0xbfb8aa3b, v0
	v_exp_f32_e32 v175, v0
	v_add_f32_e32 v0, 1.0, v161
	v_med3_f32 v161, v178, s73, v159
	v_mul_f32_e32 v161, 0xbfb8aa3b, v161
	v_exp_f32_e32 v161, v161
	v_rcp_f32_e32 v177, v0
	v_med3_f32 v0, v184, s73, v159
	v_mul_f32_e32 v0, 0xbfb8aa3b, v0
	v_exp_f32_e32 v178, v0
	v_add_f32_e32 v0, 1.0, v161
	v_med3_f32 v161, v179, s73, v159
	v_mul_f32_e32 v161, 0xbfb8aa3b, v161
	v_exp_f32_e32 v161, v161
	v_rcp_f32_e32 v180, v0
	v_med3_f32 v0, v185, s73, v159
	v_mul_f32_e32 v0, 0xbfb8aa3b, v0
	v_exp_f32_e32 v179, v0
	v_add_f32_e32 v0, 1.0, v161
	v_med3_f32 v161, v182, s73, v159
	v_mul_f32_e32 v161, 0xbfb8aa3b, v161
	v_exp_f32_e32 v161, v161
	v_rcp_f32_e32 v181, v0
	v_med3_f32 v0, v186, s73, v159
	v_mul_f32_e32 v0, 0xbfb8aa3b, v0
	v_exp_f32_e32 v182, v0
	v_add_f32_e32 v0, 1.0, v161
	v_med3_f32 v161, v183, s73, v159
	v_mul_f32_e32 v161, 0xbfb8aa3b, v161
	v_exp_f32_e32 v161, v161
	v_med3_f32 v166, v166, s73, v159
	v_rcp_f32_e32 v184, v0
	v_mul_f32_e32 v166, 0xbfb8aa3b, v166
	v_med3_f32 v0, v187, s73, v159
	v_exp_f32_e32 v166, v166
	v_mul_f32_e32 v0, 0xbfb8aa3b, v0
	v_exp_f32_e32 v183, v0
	v_add_f32_e32 v0, 1.0, v161
	v_rcp_f32_e32 v185, v0
	s_waitcnt vmcnt(1)
	v_lshlrev_b32_e32 v0, 16, v170
	v_pk_add_f32 v[166:167], v[166:167], 1.0 op_sel_hi:[1,0]
	v_med3_f32 v0, v0, s73, v159
	v_pk_add_f32 v[174:175], v[174:175], 1.0 op_sel_hi:[1,0]
	v_pk_mul_f32 v[166:167], v[166:167], v[168:169]
	v_mul_f32_e32 v0, 0xbfb8aa3b, v0
	v_pk_mul_f32 v[168:169], v[174:175], v[176:177]
	v_pk_mul_f32 v[32:33], v[32:33], v[166:167]
	v_pk_add_f32 v[166:167], v[182:183], 1.0 op_sel_hi:[1,0]
	v_exp_f32_e32 v0, v0
	v_pk_mul_f32 v[34:35], v[34:35], v[168:169]
	v_pk_add_f32 v[168:169], v[178:179], 1.0 op_sel_hi:[1,0]
	v_pk_mul_f32 v[166:167], v[166:167], v[184:185]
	v_pk_mul_f32 v[168:169], v[168:169], v[180:181]
	v_pk_mul_f32 v[30:31], v[30:31], v[166:167]
	s_waitcnt vmcnt(0)
	v_lshlrev_b32_e32 v167, 16, v162
	v_pk_mul_f32 v[28:29], v[28:29], v[168:169]
	v_lshlrev_b32_e32 v168, 16, v163
	v_and_b32_e32 v179, 0xffff0000, v163
	v_and_b32_e32 v162, 0xffff0000, v162
	v_med3_f32 v163, v167, s73, v159
	v_add_f32_e32 v0, 1.0, v0
	v_lshlrev_b32_e32 v180, 16, v172
	v_and_b32_e32 v181, 0xffff0000, v172
	v_mul_f32_e32 v163, 0xbfb8aa3b, v163
	v_rcp_f32_e32 v172, v0
	v_mov_b32_e32 v0, v162
	v_add_co_u32_e32 v162, vcc, s83, v2
	v_and_b32_e32 v161, 0xffff0000, v170
	v_exp_f32_e32 v170, v163
	v_addc_co_u32_e32 v163, vcc, 0, v3, vcc
	v_lshlrev_b32_e32 v182, 16, v164
	v_and_b32_e32 v183, 0xffff0000, v164
	v_lshlrev_b32_e32 v186, 16, v165
	v_and_b32_e32 v187, 0xffff0000, v165
	global_load_dwordx4 v[162:165], v[162:163], off
	v_med3_f32 v161, v161, s73, v159
	v_mul_f32_e32 v161, 0xbfb8aa3b, v161
	v_exp_f32_e32 v161, v161
	v_med3_f32 v0, v0, s73, v159
	v_lshlrev_b32_e32 v166, 16, v171
	v_mul_f32_e32 v0, 0xbfb8aa3b, v0
	v_and_b32_e32 v177, 0xffff0000, v171
	v_exp_f32_e32 v171, v0
	v_add_f32_e32 v0, 1.0, v161
	v_med3_f32 v161, v166, s73, v159
	v_add_co_u32_e32 v174, vcc, s84, v2
	v_mul_f32_e32 v161, 0xbfb8aa3b, v161
	s_nop 0
	v_addc_co_u32_e32 v175, vcc, 0, v3, vcc
	v_lshlrev_b32_e32 v184, 16, v173
	v_and_b32_e32 v185, 0xffff0000, v173
	v_rcp_f32_e32 v173, v0
	v_mov_b32_e32 v0, v168
	global_load_dwordx4 v[166:169], v[174:175], off
	v_exp_f32_e32 v161, v161
	v_med3_f32 v0, v0, s73, v159
	v_mul_f32_e32 v0, 0xbfb8aa3b, v0
	v_exp_f32_e32 v176, v0
	v_add_f32_e32 v0, 1.0, v161
	v_med3_f32 v161, v177, s73, v159
	v_mul_f32_e32 v161, 0xbfb8aa3b, v161
	v_exp_f32_e32 v161, v161
	v_rcp_f32_e32 v178, v0
	v_med3_f32 v0, v179, s73, v159
	v_mul_f32_e32 v0, 0xbfb8aa3b, v0
	v_exp_f32_e32 v177, v0
	v_add_f32_e32 v0, 1.0, v161
	v_med3_f32 v161, v180, s73, v159
	v_mul_f32_e32 v161, 0xbfb8aa3b, v161
	v_exp_f32_e32 v161, v161
	v_rcp_f32_e32 v179, v0
	v_med3_f32 v0, v182, s73, v159
	v_mul_f32_e32 v0, 0xbfb8aa3b, v0
	v_exp_f32_e32 v180, v0
	v_add_f32_e32 v0, 1.0, v161
	v_med3_f32 v161, v181, s73, v159
	v_mul_f32_e32 v161, 0xbfb8aa3b, v161
	v_exp_f32_e32 v161, v161
	v_rcp_f32_e32 v182, v0
	v_med3_f32 v0, v183, s73, v159
	v_mul_f32_e32 v0, 0xbfb8aa3b, v0
	v_exp_f32_e32 v181, v0
	v_add_f32_e32 v0, 1.0, v161
	v_med3_f32 v161, v184, s73, v159
	v_mul_f32_e32 v161, 0xbfb8aa3b, v161
	v_exp_f32_e32 v161, v161
	v_rcp_f32_e32 v183, v0
	v_med3_f32 v0, v186, s73, v159
	v_mul_f32_e32 v0, 0xbfb8aa3b, v0
	v_exp_f32_e32 v184, v0
	v_add_f32_e32 v0, 1.0, v161
	v_med3_f32 v161, v185, s73, v159
	v_mul_f32_e32 v161, 0xbfb8aa3b, v161
	v_exp_f32_e32 v161, v161
	v_rcp_f32_e32 v186, v0
	v_med3_f32 v0, v187, s73, v159
	v_mul_f32_e32 v0, 0xbfb8aa3b, v0
	v_exp_f32_e32 v185, v0
	v_add_f32_e32 v0, 1.0, v161
	v_rcp_f32_e32 v187, v0
	v_pk_add_f32 v[176:177], v[176:177], 1.0 op_sel_hi:[1,0]
	v_pk_add_f32 v[170:171], v[170:171], 1.0 op_sel_hi:[1,0]
	v_lshl_add_u64 v[2:3], v[2:3], 0, s[24:25]
	v_pk_mul_f32 v[170:171], v[170:171], v[172:173]
	v_pk_mul_f32 v[172:173], v[176:177], v[178:179]
	v_pk_mul_f32 v[24:25], v[24:25], v[170:171]
	v_pk_mul_f32 v[26:27], v[26:27], v[172:173]
	v_pk_add_f32 v[170:171], v[184:185], 1.0 op_sel_hi:[1,0]
	v_pk_add_f32 v[172:173], v[180:181], 1.0 op_sel_hi:[1,0]
	v_pk_mul_f32 v[170:171], v[170:171], v[186:187]
	v_pk_mul_f32 v[172:173], v[172:173], v[182:183]
	v_pk_mul_f32 v[22:23], v[22:23], v[170:171]
	v_pk_mul_f32 v[20:21], v[20:21], v[172:173]
	global_load_dwordx4 v[170:173], v[2:3], off offset:256
	s_waitcnt vmcnt(2)
; __device__ __forceinline__ float bflo(unsigned w) { return __uint_as_float(w << 16); }
; __device__ __forceinline__ float bfhi(unsigned w) { return __uint_as_float(w & 0xffff0000u); }
;     static __device__ __forceinline__ float cl(float x) { return fminf(fmaxf(x, -30.f), 30.f); }
;     __device__ __forceinline__ void mid(f32x4 (&acc)[2][2][4][2], const Unit& u, int wr, int wc, int fr, int fq) const {
;     ...
;             for (int m = 0; m < 4; ++m) { const size_t row = (size_t)(row0 + ai * HALF + m * 16);
; #pragma unroll
;                 for (int bj = 0; bj < 2; ++bj) { const int col = u.pn * BM + bj * HALF + wc * 32 + 8 * fq;
;                     const bf16_t* gp = gate + (size_t)(col >> 10) * SEC + row * 1024 + (col & 1023);
;                     const u32x4 ga = *(const u32x4*)gp, gb = *(const u32x4*)(gp + 2 * SEC);
;                     float ea[8] = {bflo(ga.x), bfhi(ga.x), bflo(ga.y), bfhi(ga.y), bflo(ga.z), bfhi(ga.z), bflo(ga.w), bfhi(ga.w)};
;                     float eb[8] = {bflo(gb.x), bfhi(gb.x), bflo(gb.y), bfhi(gb.y), bflo(gb.z), bfhi(gb.z), bflo(gb.w), bfhi(gb.w)};
;                     float r[8];
; #pragma unroll
;                     for (int e = 0; e < 8; ++e) r[e] = (1.f + __expf(-cl(eb[e]))) * __builtin_amdgcn_rcpf(1.f + __expf(-cl(ea[e])));
;                     acc[ai][bj][m][0][0] *= r[0]; acc[ai][bj][m][0][1] *= r[1]; acc[ai][bj][m][0][2] *= r[2]; acc[ai][bj][m][0][3] *= r[3];
;                     acc[ai][bj][m][1][0] *= r[4]; acc[ai][bj][m][1][1] *= r[5]; acc[ai][bj][m][1][2] *= r[6]; acc[ai][bj][m][1][3] *= r[7]; }
;                 if (m == 3) __builtin_amdgcn_sched_barrier(0); }
	v_lshlrev_b32_e32 v0, 16, v162
	v_and_b32_e32 v3, 0xffff0000, v162
	v_lshlrev_b32_e32 v161, 16, v163
	v_and_b32_e32 v176, 0xffff0000, v163
	v_lshlrev_b32_e32 v177, 16, v164
	v_and_b32_e32 v179, 0xffff0000, v164
	v_lshlrev_b32_e32 v180, 16, v165
	v_and_b32_e32 v181, 0xffff0000, v165
	global_load_dwordx4 v[162:165], v[174:175], off offset:256
	v_med3_f32 v0, v0, s73, v159
	v_mul_f32_e32 v0, 0xbfb8aa3b, v0
	v_exp_f32_e32 v0, v0
	v_med3_f32 v3, v3, s73, v159
	v_mul_f32_e32 v3, 0xbfb8aa3b, v3
	s_waitcnt vmcnt(2)
	v_and_b32_e32 v174, 0xffff0000, v166
	v_lshlrev_b32_e32 v175, 16, v167
	v_and_b32_e32 v178, 0xffff0000, v167
	v_add_f32_e32 v0, 1.0, v0
	v_exp_f32_e32 v167, v3
	v_lshlrev_b32_e32 v2, 16, v166
	v_rcp_f32_e32 v166, v0
	v_med3_f32 v0, v174, s73, v159
	v_med3_f32 v161, v161, s73, v159
	v_mul_f32_e32 v0, 0xbfb8aa3b, v0
	v_mul_f32_e32 v161, 0xbfb8aa3b, v161
	v_exp_f32_e32 v3, v0
	v_add_f32_e32 v0, 1.0, v167
	v_exp_f32_e32 v161, v161
	v_rcp_f32_e32 v167, v0
	v_med3_f32 v0, v175, s73, v159
	v_mul_f32_e32 v0, 0xbfb8aa3b, v0
	v_lshlrev_b32_e32 v182, 16, v168
	v_and_b32_e32 v183, 0xffff0000, v168
	v_exp_f32_e32 v168, v0
	v_add_f32_e32 v0, 1.0, v161
	v_med3_f32 v161, v176, s73, v159
	v_mul_f32_e32 v161, 0xbfb8aa3b, v161
	v_exp_f32_e32 v161, v161
	v_rcp_f32_e32 v174, v0
	v_med3_f32 v0, v178, s73, v159
	v_mul_f32_e32 v0, 0xbfb8aa3b, v0
	v_lshlrev_b32_e32 v184, 16, v169
	v_and_b32_e32 v185, 0xffff0000, v169
	v_exp_f32_e32 v169, v0
	v_add_f32_e32 v0, 1.0, v161
	v_med3_f32 v161, v177, s73, v159
	v_mul_f32_e32 v161, 0xbfb8aa3b, v161
	v_exp_f32_e32 v161, v161
	v_rcp_f32_e32 v175, v0
	v_med3_f32 v0, v182, s73, v159
	v_mul_f32_e32 v0, 0xbfb8aa3b, v0
	v_exp_f32_e32 v176, v0
	v_add_f32_e32 v0, 1.0, v161
	v_med3_f32 v161, v179, s73, v159
	v_mul_f32_e32 v161, 0xbfb8aa3b, v161
	v_exp_f32_e32 v161, v161
	v_rcp_f32_e32 v178, v0
	v_med3_f32 v0, v183, s73, v159
	v_mul_f32_e32 v0, 0xbfb8aa3b, v0
	v_exp_f32_e32 v177, v0
	v_add_f32_e32 v0, 1.0, v161
	v_med3_f32 v161, v180, s73, v159
	v_mul_f32_e32 v161, 0xbfb8aa3b, v161
	v_exp_f32_e32 v161, v161
	v_rcp_f32_e32 v179, v0
	v_med3_f32 v0, v184, s73, v159
	v_mul_f32_e32 v0, 0xbfb8aa3b, v0
	v_exp_f32_e32 v180, v0
	v_add_f32_e32 v0, 1.0, v161
	v_med3_f32 v161, v181, s73, v159
	v_mul_f32_e32 v161, 0xbfb8aa3b, v161
	v_med3_f32 v2, v2, s73, v159
	v_exp_f32_e32 v161, v161
	v_mul_f32_e32 v2, 0xbfb8aa3b, v2
	v_rcp_f32_e32 v182, v0
	v_exp_f32_e32 v2, v2
	v_med3_f32 v0, v185, s73, v159
	v_mul_f32_e32 v0, 0xbfb8aa3b, v0
	v_exp_f32_e32 v181, v0
	v_add_f32_e32 v0, 1.0, v161
	v_rcp_f32_e32 v183, v0
	v_pk_add_f32 v[2:3], v[2:3], 1.0 op_sel_hi:[1,0]
	s_waitcnt vmcnt(1)
	v_lshlrev_b32_e32 v0, 16, v170
	v_pk_mul_f32 v[2:3], v[2:3], v[166:167]
	v_pk_mul_f32 v[16:17], v[16:17], v[2:3]
	v_pk_add_f32 v[2:3], v[180:181], 1.0 op_sel_hi:[1,0]
	v_med3_f32 v0, v0, s73, v159
	v_pk_mul_f32 v[2:3], v[2:3], v[182:183]
	v_mul_f32_e32 v0, 0xbfb8aa3b, v0
	v_pk_add_f32 v[168:169], v[168:169], 1.0 op_sel_hi:[1,0]
	v_pk_mul_f32 v[14:15], v[14:15], v[2:3]
	v_and_b32_e32 v3, 0xffff0000, v170
	v_exp_f32_e32 v0, v0
	v_pk_mul_f32 v[166:167], v[168:169], v[174:175]
	v_pk_mul_f32 v[18:19], v[18:19], v[166:167]
	v_pk_add_f32 v[166:167], v[176:177], 1.0 op_sel_hi:[1,0]
	v_med3_f32 v3, v3, s73, v159
	v_pk_mul_f32 v[166:167], v[166:167], v[178:179]
	v_mul_f32_e32 v3, 0xbfb8aa3b, v3
	v_pk_mul_f32 v[12:13], v[12:13], v[166:167]
	v_lshlrev_b32_e32 v161, 16, v171
	v_and_b32_e32 v167, 0xffff0000, v171
	s_waitcnt vmcnt(0)
	v_and_b32_e32 v166, 0xffff0000, v162
	v_lshlrev_b32_e32 v170, 16, v163
	v_and_b32_e32 v171, 0xffff0000, v163
	v_add_f32_e32 v0, 1.0, v0
	v_exp_f32_e32 v163, v3
	v_lshlrev_b32_e32 v2, 16, v162
	v_rcp_f32_e32 v162, v0
	v_med3_f32 v0, v166, s73, v159
	v_med3_f32 v161, v161, s73, v159
	v_mul_f32_e32 v0, 0xbfb8aa3b, v0
	v_mul_f32_e32 v161, 0xbfb8aa3b, v161
	v_exp_f32_e32 v3, v0
	v_add_f32_e32 v0, 1.0, v163
	v_exp_f32_e32 v161, v161
	v_rcp_f32_e32 v163, v0
	v_med3_f32 v0, v170, s73, v159
	v_mul_f32_e32 v0, 0xbfb8aa3b, v0
	v_lshlrev_b32_e32 v174, 16, v164
	v_and_b32_e32 v175, 0xffff0000, v164
	v_exp_f32_e32 v164, v0
	v_add_f32_e32 v0, 1.0, v161
	v_med3_f32 v161, v167, s73, v159
	v_mul_f32_e32 v161, 0xbfb8aa3b, v161
	v_exp_f32_e32 v161, v161
	v_rcp_f32_e32 v166, v0
	v_med3_f32 v0, v171, s73, v159
	v_lshlrev_b32_e32 v168, 16, v172
	v_mul_f32_e32 v0, 0xbfb8aa3b, v0
	v_lshlrev_b32_e32 v176, 16, v165
	v_and_b32_e32 v177, 0xffff0000, v165
	v_exp_f32_e32 v165, v0
	v_add_f32_e32 v0, 1.0, v161
	v_med3_f32 v161, v168, s73, v159
	v_mul_f32_e32 v161, 0xbfb8aa3b, v161
	v_exp_f32_e32 v161, v161
	v_rcp_f32_e32 v167, v0
	v_med3_f32 v0, v174, s73, v159
	v_and_b32_e32 v169, 0xffff0000, v172
	v_mul_f32_e32 v0, 0xbfb8aa3b, v0
	v_exp_f32_e32 v168, v0
	v_add_f32_e32 v0, 1.0, v161
	v_med3_f32 v161, v169, s73, v159
	v_mul_f32_e32 v161, 0xbfb8aa3b, v161
	v_exp_f32_e32 v161, v161
	v_rcp_f32_e32 v170, v0
	v_med3_f32 v0, v175, s73, v159
	v_lshlrev_b32_e32 v172, 16, v173
	v_mul_f32_e32 v0, 0xbfb8aa3b, v0
	v_exp_f32_e32 v169, v0
	v_add_f32_e32 v0, 1.0, v161
	v_med3_f32 v161, v172, s73, v159
	v_mul_f32_e32 v161, 0xbfb8aa3b, v161
	v_exp_f32_e32 v161, v161
	v_rcp_f32_e32 v171, v0
	v_med3_f32 v0, v176, s73, v159
	v_and_b32_e32 v173, 0xffff0000, v173
	v_mul_f32_e32 v0, 0xbfb8aa3b, v0
	v_exp_f32_e32 v172, v0
	v_add_f32_e32 v0, 1.0, v161
	v_med3_f32 v161, v173, s73, v159
	v_mul_f32_e32 v161, 0xbfb8aa3b, v161
	v_med3_f32 v2, v2, s73, v159
	v_exp_f32_e32 v161, v161
	v_mul_f32_e32 v2, 0xbfb8aa3b, v2
	v_rcp_f32_e32 v174, v0
	v_exp_f32_e32 v2, v2
	v_med3_f32 v0, v177, s73, v159
	v_mul_f32_e32 v0, 0xbfb8aa3b, v0
	v_exp_f32_e32 v173, v0
	v_add_f32_e32 v0, 1.0, v161
	v_rcp_f32_e32 v175, v0
	v_pk_add_f32 v[164:165], v[164:165], 1.0 op_sel_hi:[1,0]
	v_pk_add_f32 v[2:3], v[2:3], 1.0 op_sel_hi:[1,0]
	s_nop 0
	v_pk_mul_f32 v[2:3], v[2:3], v[162:163]
	v_pk_mul_f32 v[162:163], v[164:165], v[166:167]
	v_pk_mul_f32 v[8:9], v[8:9], v[2:3]
	v_pk_mul_f32 v[10:11], v[10:11], v[162:163]
	v_pk_add_f32 v[2:3], v[172:173], 1.0 op_sel_hi:[1,0]
	v_pk_add_f32 v[162:163], v[168:169], 1.0 op_sel_hi:[1,0]
	v_pk_mul_f32 v[2:3], v[2:3], v[174:175]
	v_pk_mul_f32 v[162:163], v[162:163], v[170:171]
	v_pk_mul_f32 v[6:7], v[6:7], v[2:3]
	v_pk_mul_f32 v[4:5], v[4:5], v[162:163]
	s_branch .LBB0_627

; __device__ __forceinline__ unsigned cvt_pk_bf16(float lo, float hi) { unsigned r; asm volatile("v_cvt_pk_bf16_f32 %0, %1, %2" : "=v"(r) : "v"(lo), "v"(hi)); return r; }
; __device__ __forceinline__ float bflo(unsigned w) { return __uint_as_float(w << 16); }
; __device__ __forceinline__ float bfhi(unsigned w) { return __uint_as_float(w & 0xffff0000u); }
; __device__ __forceinline__ float sigmoidf_(float x) { return __builtin_amdgcn_rcpf(1.f + __expf(-x)); }
;     static __device__ __forceinline__ float cl(float x) { return fminf(fmaxf(x, -30.f), 30.f); }
;     __device__ __forceinline__ void operator()(const f32x4 (&acc)[2][2][4][2], const Unit& u, int wr, int wc, int fr, int fq) const {
;         const int row0 = u.pm * BM + wr * 64 + fr;
; #pragma unroll
;         for (int ai = 0; ai < 2; ++ai)
; #pragma unroll
;             for (int m = 0; m < 4; ++m) { const size_t row = (size_t)(row0 + ai * HALF + m * 16);
; #pragma unroll
;                 for (int bj = 0; bj < 2; ++bj) { const int col = u.pn * BM + bj * HALF + wc * 32 + 8 * fq;
;                     const u32x4 gw = *(const u32x4*)(gate + (size_t)(2 + (col >> 10)) * SEC + row * 1024 + (col & 1023));
;                     const f32x4 v0 = acc[ai][bj][m][0], v1 = acc[ai][bj][m][1];
;                     float r[8];
;                     r[0] = v0[0] * sigmoidf_(cl(bflo(gw.x))); r[1] = v0[1] * sigmoidf_(cl(bfhi(gw.x))); r[2] = v0[2] * sigmoidf_(cl(bflo(gw.y))); r[3] = v0[3] * sigmoidf_(cl(bfhi(gw.y)));
;                     r[4] = v1[0] * sigmoidf_(cl(bflo(gw.z))); r[5] = v1[1] * sigmoidf_(cl(bfhi(gw.z))); r[6] = v1[2] * sigmoidf_(cl(bflo(gw.w))); r[7] = v1[3] * sigmoidf_(cl(bfhi(gw.w)));
;                     u32x4 w; w.x = cvt_pk_bf16(r[0], r[1]); w.y = cvt_pk_bf16(r[2], r[3]); w.z = cvt_pk_bf16(r[4], r[5]); w.w = cvt_pk_bf16(r[6], r[7]);
;                     *(u32x4*)(mix + row * 2048 + col) = w; } }
;     }
.LBB0_632:
	s_lshl_b64 s[46:47], s[48:49], 26
	s_add_u32 s41, s65, s46
	v_add_u32_e32 v150, s89, v155
	s_addc_u32 s47, s66, s47
	v_ashrrev_i32_e32 v151, 31, v150
	s_add_u32 s46, s41, 0x8000000
	v_mov_b32_e32 v0, s31
	v_lshlrev_b64 v[2:3], 11, v[150:151]
	s_addc_u32 s47, s47, 0
	v_bitop3_b32 v0, v157, s86, v0 bitop3:0xc8
	v_lshl_add_u64 v[152:153], s[46:47], 0, v[2:3]
	v_lshlrev_b32_e32 v0, 1, v0
	v_lshl_add_u64 v[2:3], v[152:153], 0, v[0:1]
	global_load_dwordx4 v[162:165], v[2:3], off
	v_lshlrev_b64 v[166:167], 12, v[150:151]
	v_or_b32_e32 v148, s31, v157
	v_ashrrev_i32_e32 v149, 31, v148
	v_bitop3_b32 v2, v148, s87, v160 bitop3:0xc8
	v_lshlrev_b64 v[148:149], 1, v[148:149]
	v_lshl_add_u64 v[166:167], s[38:39], 0, v[166:167]
	v_mov_b32_e32 v3, v1
	v_lshlrev_b32_e32 v2, 1, v2
	v_lshl_add_u64 v[166:167], v[166:167], 0, v[148:149]
	v_lshl_add_u64 v[152:153], v[152:153], 0, v[2:3]
	s_andn2_b64 vcc, exec, s[0:1]
	s_mov_b64 s[0:1], -1
	s_waitcnt vmcnt(0)
	v_lshlrev_b32_e32 v169, 16, v165
	v_and_b32_e32 v165, 0xffff0000, v165
	v_lshlrev_b32_e32 v151, 16, v162
	v_and_b32_e32 v161, 0xffff0000, v162
	v_lshlrev_b32_e32 v162, 16, v163
	v_and_b32_e32 v163, 0xffff0000, v163
	v_lshlrev_b32_e32 v168, 16, v164
	v_and_b32_e32 v164, 0xffff0000, v164
	v_med3_f32 v165, v165, s73, v159
	v_med3_f32 v151, v151, s73, v159
	v_med3_f32 v161, v161, s73, v159
	v_med3_f32 v162, v162, s73, v159
	v_med3_f32 v163, v163, s73, v159
	v_med3_f32 v168, v168, s73, v159
	v_med3_f32 v164, v164, s73, v159
	v_med3_f32 v169, v169, s73, v159
	v_mul_f32_e32 v165, 0xbfb8aa3b, v165
	v_mul_f32_e32 v151, 0xbfb8aa3b, v151
	v_mul_f32_e32 v161, 0xbfb8aa3b, v161
	v_mul_f32_e32 v162, 0xbfb8aa3b, v162
	v_mul_f32_e32 v163, 0xbfb8aa3b, v163
	v_mul_f32_e32 v168, 0xbfb8aa3b, v168
	v_mul_f32_e32 v164, 0xbfb8aa3b, v164
	v_mul_f32_e32 v169, 0xbfb8aa3b, v169
	v_exp_f32_e32 v165, v165
	v_exp_f32_e32 v151, v151
	v_exp_f32_e32 v161, v161
	v_exp_f32_e32 v162, v162
	v_exp_f32_e32 v163, v163
	v_exp_f32_e32 v168, v168
	v_exp_f32_e32 v164, v164
	v_exp_f32_e32 v169, v169
	v_add_f32_e32 v165, 1.0, v165
	v_add_f32_e32 v151, 1.0, v151
	v_add_f32_e32 v161, 1.0, v161
	v_add_f32_e32 v162, 1.0, v162
	v_add_f32_e32 v163, 1.0, v163
	v_add_f32_e32 v168, 1.0, v168
	v_add_f32_e32 v164, 1.0, v164
	v_add_f32_e32 v169, 1.0, v169
	v_rcp_f32_e32 v165, v165
	v_rcp_f32_e32 v151, v151
	v_rcp_f32_e32 v161, v161
	v_rcp_f32_e32 v162, v162
	v_rcp_f32_e32 v163, v163
	v_rcp_f32_e32 v168, v168
	v_rcp_f32_e32 v164, v164
	v_rcp_f32_e32 v169, v169
	v_mul_f32_e32 v127, v127, v165
	v_mul_f32_e32 v128, v128, v151
	v_mul_f32_e32 v129, v129, v161
	v_mul_f32_e32 v130, v130, v162
	v_mul_f32_e32 v131, v131, v163
	v_mul_f32_e32 v151, v124, v168
	v_mul_f32_e32 v161, v125, v164
	v_mul_f32_e32 v162, v126, v169
	v_cvt_pk_bf16_f32 v124, v128, v129
	v_cvt_pk_bf16_f32 v125, v130, v131
	v_cvt_pk_bf16_f32 v126, v151, v161
	v_cvt_pk_bf16_f32 v127, v162, v127
	global_store_dwordx4 v[166:167], v[124:127], off
	global_load_dwordx4 v[124:127], v[152:153], off
	v_or_b32_e32 v128, 16, v150
	v_ashrrev_i32_e32 v129, 31, v128
	v_lshlrev_b64 v[130:131], 11, v[128:129]
	v_lshl_add_u64 v[130:131], s[46:47], 0, v[130:131]
	v_lshl_add_u64 v[152:153], v[130:131], 0, v[0:1]
	s_waitcnt vmcnt(0)
	v_lshlrev_b32_e32 v163, 16, v127
	v_and_b32_e32 v127, 0xffff0000, v127
	v_lshlrev_b32_e32 v151, 16, v124
	v_and_b32_e32 v124, 0xffff0000, v124
	v_lshlrev_b32_e32 v161, 16, v125
	v_and_b32_e32 v125, 0xffff0000, v125
	v_lshlrev_b32_e32 v162, 16, v126
	v_and_b32_e32 v126, 0xffff0000, v126
	v_med3_f32 v127, v127, s73, v159
	v_med3_f32 v151, v151, s73, v159
	v_med3_f32 v124, v124, s73, v159
	v_med3_f32 v161, v161, s73, v159
	v_med3_f32 v125, v125, s73, v159
	v_med3_f32 v162, v162, s73, v159
	v_med3_f32 v126, v126, s73, v159
	v_med3_f32 v163, v163, s73, v159
	v_mul_f32_e32 v127, 0xbfb8aa3b, v127
	v_mul_f32_e32 v151, 0xbfb8aa3b, v151
	v_mul_f32_e32 v124, 0xbfb8aa3b, v124
	v_mul_f32_e32 v161, 0xbfb8aa3b, v161
	v_mul_f32_e32 v125, 0xbfb8aa3b, v125
	v_mul_f32_e32 v162, 0xbfb8aa3b, v162
	v_mul_f32_e32 v126, 0xbfb8aa3b, v126
	v_mul_f32_e32 v163, 0xbfb8aa3b, v163
	v_exp_f32_e32 v127, v127
	v_exp_f32_e32 v151, v151
	v_exp_f32_e32 v124, v124
	v_exp_f32_e32 v161, v161
	v_exp_f32_e32 v125, v125
	v_exp_f32_e32 v162, v162
	v_exp_f32_e32 v126, v126
	v_exp_f32_e32 v163, v163
	v_add_f32_e32 v127, 1.0, v127
	v_add_f32_e32 v151, 1.0, v151
	v_add_f32_e32 v124, 1.0, v124
	v_add_f32_e32 v161, 1.0, v161
	v_add_f32_e32 v125, 1.0, v125
	v_add_f32_e32 v162, 1.0, v162
	v_add_f32_e32 v126, 1.0, v126
	v_add_f32_e32 v163, 1.0, v163
	v_rcp_f32_e32 v127, v127
	v_rcp_f32_e32 v151, v151
	v_rcp_f32_e32 v124, v124
	v_rcp_f32_e32 v161, v161
	v_rcp_f32_e32 v125, v125
	v_rcp_f32_e32 v162, v162
	v_rcp_f32_e32 v126, v126
	v_rcp_f32_e32 v163, v163
	v_mul_f32_e32 v119, v119, v127
	v_mul_f32_e32 v120, v120, v151
	v_mul_f32_e32 v121, v121, v124
	v_mul_f32_e32 v122, v122, v161
	v_mul_f32_e32 v123, v123, v125
	v_mul_f32_e32 v124, v116, v162
	v_mul_f32_e32 v125, v117, v126
	v_mul_f32_e32 v126, v118, v163
	v_cvt_pk_bf16_f32 v116, v120, v121
	v_cvt_pk_bf16_f32 v117, v122, v123
	v_cvt_pk_bf16_f32 v118, v124, v125
	v_cvt_pk_bf16_f32 v119, v126, v119
	global_store_dwordx4 v[166:167], v[116:119], off offset:256
	global_load_dwordx4 v[116:119], v[152:153], off
	v_lshlrev_b64 v[120:121], 12, v[128:129]
	v_lshl_add_u64 v[120:121], s[38:39], 0, v[120:121]
	v_lshl_add_u64 v[120:121], v[120:121], 0, v[148:149]
	v_lshl_add_u64 v[122:123], v[130:131], 0, v[2:3]
	s_waitcnt vmcnt(0)
; __device__ __forceinline__ unsigned cvt_pk_bf16(float lo, float hi) { unsigned r; asm volatile("v_cvt_pk_bf16_f32 %0, %1, %2" : "=v"(r) : "v"(lo), "v"(hi)); return r; }
; __device__ __forceinline__ float bflo(unsigned w) { return __uint_as_float(w << 16); }
; __device__ __forceinline__ float bfhi(unsigned w) { return __uint_as_float(w & 0xffff0000u); }
; __device__ __forceinline__ float sigmoidf_(float x) { return __builtin_amdgcn_rcpf(1.f + __expf(-x)); }
;     static __device__ __forceinline__ float cl(float x) { return fminf(fmaxf(x, -30.f), 30.f); }
;     __device__ __forceinline__ void operator()(const f32x4 (&acc)[2][2][4][2], const Unit& u, int wr, int wc, int fr, int fq) const {
;     ...
;             for (int m = 0; m < 4; ++m) { const size_t row = (size_t)(row0 + ai * HALF + m * 16);
; #pragma unroll
;                 for (int bj = 0; bj < 2; ++bj) { const int col = u.pn * BM + bj * HALF + wc * 32 + 8 * fq;
;                     const u32x4 gw = *(const u32x4*)(gate + (size_t)(2 + (col >> 10)) * SEC + row * 1024 + (col & 1023));
;                     const f32x4 v0 = acc[ai][bj][m][0], v1 = acc[ai][bj][m][1];
;                     float r[8];
;                     r[0] = v0[0] * sigmoidf_(cl(bflo(gw.x))); r[1] = v0[1] * sigmoidf_(cl(bfhi(gw.x))); r[2] = v0[2] * sigmoidf_(cl(bflo(gw.y))); r[3] = v0[3] * sigmoidf_(cl(bfhi(gw.y)));
;                     r[4] = v1[0] * sigmoidf_(cl(bflo(gw.z))); r[5] = v1[1] * sigmoidf_(cl(bfhi(gw.z))); r[6] = v1[2] * sigmoidf_(cl(bflo(gw.w))); r[7] = v1[3] * sigmoidf_(cl(bfhi(gw.w)));
;                     u32x4 w; w.x = cvt_pk_bf16(r[0], r[1]); w.y = cvt_pk_bf16(r[2], r[3]); w.z = cvt_pk_bf16(r[4], r[5]); w.w = cvt_pk_bf16(r[6], r[7]);
;                     *(u32x4*)(mix + row * 2048 + col) = w; } }
	v_lshlrev_b32_e32 v127, 16, v119
	v_and_b32_e32 v119, 0xffff0000, v119
	v_lshlrev_b32_e32 v124, 16, v116
	v_and_b32_e32 v116, 0xffff0000, v116
	v_lshlrev_b32_e32 v125, 16, v117
	v_and_b32_e32 v117, 0xffff0000, v117
	v_lshlrev_b32_e32 v126, 16, v118
	v_and_b32_e32 v118, 0xffff0000, v118
	v_med3_f32 v119, v119, s73, v159
	v_med3_f32 v124, v124, s73, v159
	v_med3_f32 v116, v116, s73, v159
	v_med3_f32 v125, v125, s73, v159
	v_med3_f32 v117, v117, s73, v159
	v_med3_f32 v126, v126, s73, v159
	v_med3_f32 v118, v118, s73, v159
	v_med3_f32 v127, v127, s73, v159
	v_mul_f32_e32 v119, 0xbfb8aa3b, v119
	v_mul_f32_e32 v124, 0xbfb8aa3b, v124
	v_mul_f32_e32 v116, 0xbfb8aa3b, v116
	v_mul_f32_e32 v125, 0xbfb8aa3b, v125
	v_mul_f32_e32 v117, 0xbfb8aa3b, v117
	v_mul_f32_e32 v126, 0xbfb8aa3b, v126
	v_mul_f32_e32 v118, 0xbfb8aa3b, v118
	v_mul_f32_e32 v127, 0xbfb8aa3b, v127
	v_exp_f32_e32 v119, v119
	v_exp_f32_e32 v124, v124
	v_exp_f32_e32 v116, v116
	v_exp_f32_e32 v125, v125
	v_exp_f32_e32 v117, v117
	v_exp_f32_e32 v126, v126
	v_exp_f32_e32 v118, v118
	v_exp_f32_e32 v127, v127
	v_add_f32_e32 v119, 1.0, v119
	v_add_f32_e32 v124, 1.0, v124
	v_add_f32_e32 v116, 1.0, v116
	v_add_f32_e32 v125, 1.0, v125
	v_add_f32_e32 v117, 1.0, v117
	v_add_f32_e32 v126, 1.0, v126
	v_add_f32_e32 v118, 1.0, v118
	v_add_f32_e32 v127, 1.0, v127
	v_rcp_f32_e32 v119, v119
	v_rcp_f32_e32 v124, v124
	v_rcp_f32_e32 v116, v116
	v_rcp_f32_e32 v125, v125
	v_rcp_f32_e32 v117, v117
	v_rcp_f32_e32 v126, v126
	v_rcp_f32_e32 v118, v118
	v_rcp_f32_e32 v127, v127
	v_mul_f32_e32 v111, v111, v119
	v_mul_f32_e32 v112, v112, v124
	v_mul_f32_e32 v113, v113, v116
	v_mul_f32_e32 v114, v114, v125
	v_mul_f32_e32 v115, v115, v117
	v_mul_f32_e32 v116, v108, v126
	v_mul_f32_e32 v117, v109, v118
	v_mul_f32_e32 v118, v110, v127
	v_cvt_pk_bf16_f32 v108, v112, v113
	v_cvt_pk_bf16_f32 v109, v114, v115
	v_cvt_pk_bf16_f32 v110, v116, v117
	v_cvt_pk_bf16_f32 v111, v118, v111
	global_store_dwordx4 v[120:121], v[108:111], off
	global_load_dwordx4 v[108:111], v[122:123], off
	v_or_b32_e32 v112, 32, v150
	v_ashrrev_i32_e32 v113, 31, v112
	v_lshlrev_b64 v[114:115], 11, v[112:113]
	v_lshl_add_u64 v[114:115], s[46:47], 0, v[114:115]
	v_lshl_add_u64 v[116:117], v[114:115], 0, v[0:1]
	s_waitcnt vmcnt(0)
	v_lshlrev_b32_e32 v123, 16, v111
	v_and_b32_e32 v111, 0xffff0000, v111
	v_lshlrev_b32_e32 v118, 16, v108
	v_and_b32_e32 v108, 0xffff0000, v108
	v_lshlrev_b32_e32 v119, 16, v109
	v_and_b32_e32 v109, 0xffff0000, v109
	v_lshlrev_b32_e32 v122, 16, v110
	v_and_b32_e32 v110, 0xffff0000, v110
	v_med3_f32 v111, v111, s73, v159
	v_med3_f32 v118, v118, s73, v159
	v_med3_f32 v108, v108, s73, v159
	v_med3_f32 v119, v119, s73, v159
	v_med3_f32 v109, v109, s73, v159
	v_med3_f32 v122, v122, s73, v159
	v_med3_f32 v110, v110, s73, v159
	v_med3_f32 v123, v123, s73, v159
	v_mul_f32_e32 v111, 0xbfb8aa3b, v111
	v_mul_f32_e32 v118, 0xbfb8aa3b, v118
	v_mul_f32_e32 v108, 0xbfb8aa3b, v108
	v_mul_f32_e32 v119, 0xbfb8aa3b, v119
	v_mul_f32_e32 v109, 0xbfb8aa3b, v109
	v_mul_f32_e32 v122, 0xbfb8aa3b, v122
	v_mul_f32_e32 v110, 0xbfb8aa3b, v110
	v_mul_f32_e32 v123, 0xbfb8aa3b, v123
	v_exp_f32_e32 v111, v111
	v_exp_f32_e32 v118, v118
	v_exp_f32_e32 v108, v108
	v_exp_f32_e32 v119, v119
	v_exp_f32_e32 v109, v109
	v_exp_f32_e32 v122, v122
	v_exp_f32_e32 v110, v110
	v_exp_f32_e32 v123, v123
	v_add_f32_e32 v111, 1.0, v111
	v_add_f32_e32 v118, 1.0, v118
	v_add_f32_e32 v108, 1.0, v108
	v_add_f32_e32 v119, 1.0, v119
	v_add_f32_e32 v109, 1.0, v109
	v_add_f32_e32 v122, 1.0, v122
	v_add_f32_e32 v110, 1.0, v110
	v_add_f32_e32 v123, 1.0, v123
	v_rcp_f32_e32 v111, v111
	v_rcp_f32_e32 v118, v118
	v_rcp_f32_e32 v108, v108
	v_rcp_f32_e32 v119, v119
	v_rcp_f32_e32 v109, v109
	v_rcp_f32_e32 v122, v122
	v_rcp_f32_e32 v110, v110
	v_rcp_f32_e32 v123, v123
	v_mul_f32_e32 v103, v103, v111
	v_mul_f32_e32 v104, v104, v118
	v_mul_f32_e32 v105, v105, v108
	v_mul_f32_e32 v106, v106, v119
	v_mul_f32_e32 v107, v107, v109
	v_mul_f32_e32 v108, v100, v122
	v_mul_f32_e32 v109, v101, v110
	v_mul_f32_e32 v110, v102, v123
	v_cvt_pk_bf16_f32 v100, v104, v105
	v_cvt_pk_bf16_f32 v101, v106, v107
	v_cvt_pk_bf16_f32 v102, v108, v109
	v_cvt_pk_bf16_f32 v103, v110, v103
	global_store_dwordx4 v[120:121], v[100:103], off offset:256
	global_load_dwordx4 v[100:103], v[116:117], off
	v_lshlrev_b64 v[104:105], 12, v[112:113]
	v_lshl_add_u64 v[104:105], s[38:39], 0, v[104:105]
	v_lshl_add_u64 v[104:105], v[104:105], 0, v[148:149]
	v_lshl_add_u64 v[106:107], v[114:115], 0, v[2:3]
	s_waitcnt vmcnt(0)
	v_lshlrev_b32_e32 v111, 16, v103
	v_and_b32_e32 v103, 0xffff0000, v103
	v_lshlrev_b32_e32 v108, 16, v100
	v_and_b32_e32 v100, 0xffff0000, v100
	v_lshlrev_b32_e32 v109, 16, v101
	v_and_b32_e32 v101, 0xffff0000, v101
	v_lshlrev_b32_e32 v110, 16, v102
	v_and_b32_e32 v102, 0xffff0000, v102
	v_med3_f32 v103, v103, s73, v159
	v_med3_f32 v108, v108, s73, v159
	v_med3_f32 v100, v100, s73, v159
	v_med3_f32 v109, v109, s73, v159
	v_med3_f32 v101, v101, s73, v159
	v_med3_f32 v110, v110, s73, v159
	v_med3_f32 v102, v102, s73, v159
	v_med3_f32 v111, v111, s73, v159
	v_mul_f32_e32 v103, 0xbfb8aa3b, v103
	v_mul_f32_e32 v108, 0xbfb8aa3b, v108
	v_mul_f32_e32 v100, 0xbfb8aa3b, v100
	v_mul_f32_e32 v109, 0xbfb8aa3b, v109
	v_mul_f32_e32 v101, 0xbfb8aa3b, v101
	v_mul_f32_e32 v110, 0xbfb8aa3b, v110
	v_mul_f32_e32 v102, 0xbfb8aa3b, v102
	v_mul_f32_e32 v111, 0xbfb8aa3b, v111
	v_exp_f32_e32 v103, v103
	v_exp_f32_e32 v108, v108
	v_exp_f32_e32 v100, v100
	v_exp_f32_e32 v109, v109
	v_exp_f32_e32 v101, v101
	v_exp_f32_e32 v110, v110
	v_exp_f32_e32 v102, v102
	v_exp_f32_e32 v111, v111
	v_add_f32_e32 v103, 1.0, v103
	v_add_f32_e32 v108, 1.0, v108
	v_add_f32_e32 v100, 1.0, v100
	v_add_f32_e32 v109, 1.0, v109
	v_add_f32_e32 v101, 1.0, v101
	v_add_f32_e32 v110, 1.0, v110
	v_add_f32_e32 v102, 1.0, v102
	v_add_f32_e32 v111, 1.0, v111
	v_rcp_f32_e32 v103, v103
	v_rcp_f32_e32 v108, v108
	v_rcp_f32_e32 v100, v100
	v_rcp_f32_e32 v109, v109
	v_rcp_f32_e32 v101, v101
	v_rcp_f32_e32 v110, v110
	v_rcp_f32_e32 v102, v102
	v_rcp_f32_e32 v111, v111
	v_mul_f32_e32 v95, v95, v103
	v_mul_f32_e32 v96, v96, v108
	v_mul_f32_e32 v97, v97, v100
	v_mul_f32_e32 v98, v98, v109
	v_mul_f32_e32 v99, v99, v101
	v_mul_f32_e32 v100, v92, v110
	v_mul_f32_e32 v101, v93, v102
	v_mul_f32_e32 v102, v94, v111
	v_cvt_pk_bf16_f32 v92, v96, v97
	v_cvt_pk_bf16_f32 v93, v98, v99
	v_cvt_pk_bf16_f32 v94, v100, v101
	v_cvt_pk_bf16_f32 v95, v102, v95
	global_store_dwordx4 v[104:105], v[92:95], off
	global_load_dwordx4 v[92:95], v[106:107], off
	v_or_b32_e32 v96, 48, v150
	v_ashrrev_i32_e32 v97, 31, v96
	v_lshlrev_b64 v[98:99], 11, v[96:97]
	v_lshl_add_u64 v[98:99], s[46:47], 0, v[98:99]
	v_lshl_add_u64 v[100:101], v[98:99], 0, v[0:1]
	s_waitcnt vmcnt(0)
; __device__ __forceinline__ unsigned cvt_pk_bf16(float lo, float hi) { unsigned r; asm volatile("v_cvt_pk_bf16_f32 %0, %1, %2" : "=v"(r) : "v"(lo), "v"(hi)); return r; }
; __device__ __forceinline__ float bflo(unsigned w) { return __uint_as_float(w << 16); }
; __device__ __forceinline__ float bfhi(unsigned w) { return __uint_as_float(w & 0xffff0000u); }
; __device__ __forceinline__ float sigmoidf_(float x) { return __builtin_amdgcn_rcpf(1.f + __expf(-x)); }
;     static __device__ __forceinline__ float cl(float x) { return fminf(fmaxf(x, -30.f), 30.f); }
;     __device__ __forceinline__ void operator()(const f32x4 (&acc)[2][2][4][2], const Unit& u, int wr, int wc, int fr, int fq) const {
;     ...
;             for (int m = 0; m < 4; ++m) { const size_t row = (size_t)(row0 + ai * HALF + m * 16);
; #pragma unroll
;                 for (int bj = 0; bj < 2; ++bj) { const int col = u.pn * BM + bj * HALF + wc * 32 + 8 * fq;
;                     const u32x4 gw = *(const u32x4*)(gate + (size_t)(2 + (col >> 10)) * SEC + row * 1024 + (col & 1023));
;                     const f32x4 v0 = acc[ai][bj][m][0], v1 = acc[ai][bj][m][1];
;                     float r[8];
;                     r[0] = v0[0] * sigmoidf_(cl(bflo(gw.x))); r[1] = v0[1] * sigmoidf_(cl(bfhi(gw.x))); r[2] = v0[2] * sigmoidf_(cl(bflo(gw.y))); r[3] = v0[3] * sigmoidf_(cl(bfhi(gw.y)));
;                     r[4] = v1[0] * sigmoidf_(cl(bflo(gw.z))); r[5] = v1[1] * sigmoidf_(cl(bfhi(gw.z))); r[6] = v1[2] * sigmoidf_(cl(bflo(gw.w))); r[7] = v1[3] * sigmoidf_(cl(bfhi(gw.w)));
;                     u32x4 w; w.x = cvt_pk_bf16(r[0], r[1]); w.y = cvt_pk_bf16(r[2], r[3]); w.z = cvt_pk_bf16(r[4], r[5]); w.w = cvt_pk_bf16(r[6], r[7]);
;                     *(u32x4*)(mix + row * 2048 + col) = w; } }
	v_lshlrev_b32_e32 v107, 16, v95
	v_and_b32_e32 v95, 0xffff0000, v95
	v_lshlrev_b32_e32 v102, 16, v92
	v_and_b32_e32 v92, 0xffff0000, v92
	v_lshlrev_b32_e32 v103, 16, v93
	v_and_b32_e32 v93, 0xffff0000, v93
	v_lshlrev_b32_e32 v106, 16, v94
	v_and_b32_e32 v94, 0xffff0000, v94
	v_med3_f32 v95, v95, s73, v159
	v_med3_f32 v102, v102, s73, v159
	v_med3_f32 v92, v92, s73, v159
	v_med3_f32 v103, v103, s73, v159
	v_med3_f32 v93, v93, s73, v159
	v_med3_f32 v106, v106, s73, v159
	v_med3_f32 v94, v94, s73, v159
	v_med3_f32 v107, v107, s73, v159
	v_mul_f32_e32 v95, 0xbfb8aa3b, v95
	v_mul_f32_e32 v102, 0xbfb8aa3b, v102
	v_mul_f32_e32 v92, 0xbfb8aa3b, v92
	v_mul_f32_e32 v103, 0xbfb8aa3b, v103
	v_mul_f32_e32 v93, 0xbfb8aa3b, v93
	v_mul_f32_e32 v106, 0xbfb8aa3b, v106
	v_mul_f32_e32 v94, 0xbfb8aa3b, v94
	v_mul_f32_e32 v107, 0xbfb8aa3b, v107
	v_exp_f32_e32 v95, v95
	v_exp_f32_e32 v102, v102
	v_exp_f32_e32 v92, v92
	v_exp_f32_e32 v103, v103
	v_exp_f32_e32 v93, v93
	v_exp_f32_e32 v106, v106
	v_exp_f32_e32 v94, v94
	v_exp_f32_e32 v107, v107
	v_add_f32_e32 v95, 1.0, v95
	v_add_f32_e32 v102, 1.0, v102
	v_add_f32_e32 v92, 1.0, v92
	v_add_f32_e32 v103, 1.0, v103
	v_add_f32_e32 v93, 1.0, v93
	v_add_f32_e32 v106, 1.0, v106
	v_add_f32_e32 v94, 1.0, v94
	v_add_f32_e32 v107, 1.0, v107
	v_rcp_f32_e32 v95, v95
	v_rcp_f32_e32 v102, v102
	v_rcp_f32_e32 v92, v92
	v_rcp_f32_e32 v103, v103
	v_rcp_f32_e32 v93, v93
	v_rcp_f32_e32 v106, v106
	v_rcp_f32_e32 v94, v94
	v_rcp_f32_e32 v107, v107
	v_mul_f32_e32 v87, v87, v95
	v_mul_f32_e32 v88, v88, v102
	v_mul_f32_e32 v89, v89, v92
	v_mul_f32_e32 v90, v90, v103
	v_mul_f32_e32 v91, v91, v93
	v_mul_f32_e32 v92, v84, v106
	v_mul_f32_e32 v93, v85, v94
	v_mul_f32_e32 v94, v86, v107
	v_cvt_pk_bf16_f32 v84, v88, v89
	v_cvt_pk_bf16_f32 v85, v90, v91
	v_cvt_pk_bf16_f32 v86, v92, v93
	v_cvt_pk_bf16_f32 v87, v94, v87
	global_store_dwordx4 v[104:105], v[84:87], off offset:256
	global_load_dwordx4 v[84:87], v[100:101], off
	v_lshlrev_b64 v[88:89], 12, v[96:97]
	v_lshl_add_u64 v[88:89], s[38:39], 0, v[88:89]
	v_lshl_add_u64 v[88:89], v[88:89], 0, v[148:149]
	v_lshl_add_u64 v[90:91], v[98:99], 0, v[2:3]
	s_waitcnt vmcnt(0)
	v_lshlrev_b32_e32 v95, 16, v87
	v_and_b32_e32 v87, 0xffff0000, v87
	v_lshlrev_b32_e32 v92, 16, v84
	v_and_b32_e32 v84, 0xffff0000, v84
	v_lshlrev_b32_e32 v93, 16, v85
	v_and_b32_e32 v85, 0xffff0000, v85
	v_lshlrev_b32_e32 v94, 16, v86
	v_and_b32_e32 v86, 0xffff0000, v86
	v_med3_f32 v87, v87, s73, v159
	v_med3_f32 v92, v92, s73, v159
	v_med3_f32 v84, v84, s73, v159
	v_med3_f32 v93, v93, s73, v159
	v_med3_f32 v85, v85, s73, v159
	v_med3_f32 v94, v94, s73, v159
	v_med3_f32 v86, v86, s73, v159
	v_med3_f32 v95, v95, s73, v159
	v_mul_f32_e32 v87, 0xbfb8aa3b, v87
	v_mul_f32_e32 v92, 0xbfb8aa3b, v92
	v_mul_f32_e32 v84, 0xbfb8aa3b, v84
	v_mul_f32_e32 v93, 0xbfb8aa3b, v93
	v_mul_f32_e32 v85, 0xbfb8aa3b, v85
	v_mul_f32_e32 v94, 0xbfb8aa3b, v94
	v_mul_f32_e32 v86, 0xbfb8aa3b, v86
	v_mul_f32_e32 v95, 0xbfb8aa3b, v95
	v_exp_f32_e32 v87, v87
	v_exp_f32_e32 v92, v92
	v_exp_f32_e32 v84, v84
	v_exp_f32_e32 v93, v93
	v_exp_f32_e32 v85, v85
	v_exp_f32_e32 v94, v94
	v_exp_f32_e32 v86, v86
	v_exp_f32_e32 v95, v95
	v_add_f32_e32 v87, 1.0, v87
	v_add_f32_e32 v92, 1.0, v92
	v_add_f32_e32 v84, 1.0, v84
	v_add_f32_e32 v93, 1.0, v93
	v_add_f32_e32 v85, 1.0, v85
	v_add_f32_e32 v94, 1.0, v94
	v_add_f32_e32 v86, 1.0, v86
	v_add_f32_e32 v95, 1.0, v95
	v_rcp_f32_e32 v87, v87
	v_rcp_f32_e32 v92, v92
	v_rcp_f32_e32 v84, v84
	v_rcp_f32_e32 v93, v93
	v_rcp_f32_e32 v85, v85
	v_rcp_f32_e32 v94, v94
	v_rcp_f32_e32 v86, v86
	v_rcp_f32_e32 v95, v95
	v_mul_f32_e32 v79, v79, v87
	v_mul_f32_e32 v80, v80, v92
	v_mul_f32_e32 v81, v81, v84
	v_mul_f32_e32 v82, v82, v93
	v_mul_f32_e32 v83, v83, v85
	v_mul_f32_e32 v84, v76, v94
	v_mul_f32_e32 v85, v77, v86
	v_mul_f32_e32 v86, v78, v95
	v_cvt_pk_bf16_f32 v76, v80, v81
	v_cvt_pk_bf16_f32 v77, v82, v83
	v_cvt_pk_bf16_f32 v78, v84, v85
	v_cvt_pk_bf16_f32 v79, v86, v79
	global_store_dwordx4 v[88:89], v[76:79], off
	global_load_dwordx4 v[76:79], v[90:91], off
	v_add_u32_e32 v80, 0x80, v150
	v_ashrrev_i32_e32 v81, 31, v80
	v_lshlrev_b64 v[82:83], 11, v[80:81]
	v_lshl_add_u64 v[82:83], s[46:47], 0, v[82:83]
	v_lshl_add_u64 v[84:85], v[82:83], 0, v[0:1]
	s_waitcnt vmcnt(0)
	v_lshlrev_b32_e32 v91, 16, v79
	v_and_b32_e32 v79, 0xffff0000, v79
	v_lshlrev_b32_e32 v86, 16, v76
	v_and_b32_e32 v76, 0xffff0000, v76
	v_lshlrev_b32_e32 v87, 16, v77
	v_and_b32_e32 v77, 0xffff0000, v77
	v_lshlrev_b32_e32 v90, 16, v78
	v_and_b32_e32 v78, 0xffff0000, v78
	v_med3_f32 v79, v79, s73, v159
	v_med3_f32 v86, v86, s73, v159
	v_med3_f32 v76, v76, s73, v159
	v_med3_f32 v87, v87, s73, v159
	v_med3_f32 v77, v77, s73, v159
	v_med3_f32 v90, v90, s73, v159
	v_med3_f32 v78, v78, s73, v159
	v_med3_f32 v91, v91, s73, v159
	v_mul_f32_e32 v79, 0xbfb8aa3b, v79
	v_mul_f32_e32 v86, 0xbfb8aa3b, v86
	v_mul_f32_e32 v76, 0xbfb8aa3b, v76
	v_mul_f32_e32 v87, 0xbfb8aa3b, v87
	v_mul_f32_e32 v77, 0xbfb8aa3b, v77
	v_mul_f32_e32 v90, 0xbfb8aa3b, v90
	v_mul_f32_e32 v78, 0xbfb8aa3b, v78
	v_mul_f32_e32 v91, 0xbfb8aa3b, v91
	v_exp_f32_e32 v79, v79
	v_exp_f32_e32 v86, v86
	v_exp_f32_e32 v76, v76
	v_exp_f32_e32 v87, v87
	v_exp_f32_e32 v77, v77
	v_exp_f32_e32 v90, v90
	v_exp_f32_e32 v78, v78
	v_exp_f32_e32 v91, v91
	v_add_f32_e32 v79, 1.0, v79
	v_add_f32_e32 v86, 1.0, v86
	v_add_f32_e32 v76, 1.0, v76
	v_add_f32_e32 v87, 1.0, v87
	v_add_f32_e32 v77, 1.0, v77
	v_add_f32_e32 v90, 1.0, v90
	v_add_f32_e32 v78, 1.0, v78
	v_add_f32_e32 v91, 1.0, v91
	v_rcp_f32_e32 v79, v79
	v_rcp_f32_e32 v86, v86
	v_rcp_f32_e32 v76, v76
	v_rcp_f32_e32 v87, v87
	v_rcp_f32_e32 v77, v77
	v_rcp_f32_e32 v90, v90
	v_rcp_f32_e32 v78, v78
	v_rcp_f32_e32 v91, v91
	v_mul_f32_e32 v71, v71, v79
	v_mul_f32_e32 v72, v72, v86
	v_mul_f32_e32 v73, v73, v76
	v_mul_f32_e32 v74, v74, v87
	v_mul_f32_e32 v75, v75, v77
	v_mul_f32_e32 v76, v68, v90
	v_mul_f32_e32 v77, v69, v78
	v_mul_f32_e32 v78, v70, v91
	v_cvt_pk_bf16_f32 v68, v72, v73
	v_cvt_pk_bf16_f32 v69, v74, v75
	v_cvt_pk_bf16_f32 v70, v76, v77
	v_cvt_pk_bf16_f32 v71, v78, v71
	global_store_dwordx4 v[88:89], v[68:71], off offset:256
	global_load_dwordx4 v[68:71], v[84:85], off
	v_lshlrev_b64 v[72:73], 12, v[80:81]
	v_lshl_add_u64 v[72:73], s[38:39], 0, v[72:73]
	v_lshl_add_u64 v[72:73], v[72:73], 0, v[148:149]
	v_lshl_add_u64 v[74:75], v[82:83], 0, v[2:3]
	s_waitcnt vmcnt(0)
; __device__ __forceinline__ unsigned cvt_pk_bf16(float lo, float hi) { unsigned r; asm volatile("v_cvt_pk_bf16_f32 %0, %1, %2" : "=v"(r) : "v"(lo), "v"(hi)); return r; }
; __device__ __forceinline__ float bflo(unsigned w) { return __uint_as_float(w << 16); }
; __device__ __forceinline__ float bfhi(unsigned w) { return __uint_as_float(w & 0xffff0000u); }
; __device__ __forceinline__ float sigmoidf_(float x) { return __builtin_amdgcn_rcpf(1.f + __expf(-x)); }
;     static __device__ __forceinline__ float cl(float x) { return fminf(fmaxf(x, -30.f), 30.f); }
;     __device__ __forceinline__ void operator()(const f32x4 (&acc)[2][2][4][2], const Unit& u, int wr, int wc, int fr, int fq) const {
;     ...
;             for (int m = 0; m < 4; ++m) { const size_t row = (size_t)(row0 + ai * HALF + m * 16);
; #pragma unroll
;                 for (int bj = 0; bj < 2; ++bj) { const int col = u.pn * BM + bj * HALF + wc * 32 + 8 * fq;
;                     const u32x4 gw = *(const u32x4*)(gate + (size_t)(2 + (col >> 10)) * SEC + row * 1024 + (col & 1023));
;                     const f32x4 v0 = acc[ai][bj][m][0], v1 = acc[ai][bj][m][1];
;                     float r[8];
;                     r[0] = v0[0] * sigmoidf_(cl(bflo(gw.x))); r[1] = v0[1] * sigmoidf_(cl(bfhi(gw.x))); r[2] = v0[2] * sigmoidf_(cl(bflo(gw.y))); r[3] = v0[3] * sigmoidf_(cl(bfhi(gw.y)));
;                     r[4] = v1[0] * sigmoidf_(cl(bflo(gw.z))); r[5] = v1[1] * sigmoidf_(cl(bfhi(gw.z))); r[6] = v1[2] * sigmoidf_(cl(bflo(gw.w))); r[7] = v1[3] * sigmoidf_(cl(bfhi(gw.w)));
;                     u32x4 w; w.x = cvt_pk_bf16(r[0], r[1]); w.y = cvt_pk_bf16(r[2], r[3]); w.z = cvt_pk_bf16(r[4], r[5]); w.w = cvt_pk_bf16(r[6], r[7]);
;                     *(u32x4*)(mix + row * 2048 + col) = w; } }
	v_lshlrev_b32_e32 v79, 16, v71
	v_and_b32_e32 v71, 0xffff0000, v71
	v_lshlrev_b32_e32 v76, 16, v68
	v_and_b32_e32 v68, 0xffff0000, v68
	v_lshlrev_b32_e32 v77, 16, v69
	v_and_b32_e32 v69, 0xffff0000, v69
	v_lshlrev_b32_e32 v78, 16, v70
	v_and_b32_e32 v70, 0xffff0000, v70
	v_med3_f32 v71, v71, s73, v159
	v_med3_f32 v76, v76, s73, v159
	v_med3_f32 v68, v68, s73, v159
	v_med3_f32 v77, v77, s73, v159
	v_med3_f32 v69, v69, s73, v159
	v_med3_f32 v78, v78, s73, v159
	v_med3_f32 v70, v70, s73, v159
	v_med3_f32 v79, v79, s73, v159
	v_mul_f32_e32 v71, 0xbfb8aa3b, v71
	v_mul_f32_e32 v76, 0xbfb8aa3b, v76
	v_mul_f32_e32 v68, 0xbfb8aa3b, v68
	v_mul_f32_e32 v77, 0xbfb8aa3b, v77
	v_mul_f32_e32 v69, 0xbfb8aa3b, v69
	v_mul_f32_e32 v78, 0xbfb8aa3b, v78
	v_mul_f32_e32 v70, 0xbfb8aa3b, v70
	v_mul_f32_e32 v79, 0xbfb8aa3b, v79
	v_exp_f32_e32 v71, v71
	v_exp_f32_e32 v76, v76
	v_exp_f32_e32 v68, v68
	v_exp_f32_e32 v77, v77
	v_exp_f32_e32 v69, v69
	v_exp_f32_e32 v78, v78
	v_exp_f32_e32 v70, v70
	v_exp_f32_e32 v79, v79
	v_add_f32_e32 v71, 1.0, v71
	v_add_f32_e32 v76, 1.0, v76
	v_add_f32_e32 v68, 1.0, v68
	v_add_f32_e32 v77, 1.0, v77
	v_add_f32_e32 v69, 1.0, v69
	v_add_f32_e32 v78, 1.0, v78
	v_add_f32_e32 v70, 1.0, v70
	v_add_f32_e32 v79, 1.0, v79
	v_rcp_f32_e32 v71, v71
	v_rcp_f32_e32 v76, v76
	v_rcp_f32_e32 v68, v68
	v_rcp_f32_e32 v77, v77
	v_rcp_f32_e32 v69, v69
	v_rcp_f32_e32 v78, v78
	v_rcp_f32_e32 v70, v70
	v_rcp_f32_e32 v79, v79
	v_mul_f32_e32 v63, v63, v71
	v_mul_f32_e32 v64, v64, v76
	v_mul_f32_e32 v65, v65, v68
	v_mul_f32_e32 v66, v66, v77
	v_mul_f32_e32 v67, v67, v69
	v_mul_f32_e32 v68, v60, v78
	v_mul_f32_e32 v69, v61, v70
	v_mul_f32_e32 v70, v62, v79
	v_cvt_pk_bf16_f32 v60, v64, v65
	v_cvt_pk_bf16_f32 v61, v66, v67
	v_cvt_pk_bf16_f32 v62, v68, v69
	v_cvt_pk_bf16_f32 v63, v70, v63
	global_store_dwordx4 v[72:73], v[60:63], off
	global_load_dwordx4 v[60:63], v[74:75], off
	v_add_u32_e32 v64, 0x90, v150
	v_ashrrev_i32_e32 v65, 31, v64
	v_lshlrev_b64 v[66:67], 11, v[64:65]
	v_lshl_add_u64 v[66:67], s[46:47], 0, v[66:67]
	v_lshl_add_u64 v[68:69], v[66:67], 0, v[0:1]
	s_waitcnt vmcnt(0)
	v_lshlrev_b32_e32 v75, 16, v63
	v_and_b32_e32 v63, 0xffff0000, v63
	v_lshlrev_b32_e32 v70, 16, v60
	v_and_b32_e32 v60, 0xffff0000, v60
	v_lshlrev_b32_e32 v71, 16, v61
	v_and_b32_e32 v61, 0xffff0000, v61
	v_lshlrev_b32_e32 v74, 16, v62
	v_and_b32_e32 v62, 0xffff0000, v62
	v_med3_f32 v63, v63, s73, v159
	v_med3_f32 v70, v70, s73, v159
	v_med3_f32 v60, v60, s73, v159
	v_med3_f32 v71, v71, s73, v159
	v_med3_f32 v61, v61, s73, v159
	v_med3_f32 v74, v74, s73, v159
	v_med3_f32 v62, v62, s73, v159
	v_med3_f32 v75, v75, s73, v159
	v_mul_f32_e32 v63, 0xbfb8aa3b, v63
	v_mul_f32_e32 v70, 0xbfb8aa3b, v70
	v_mul_f32_e32 v60, 0xbfb8aa3b, v60
	v_mul_f32_e32 v71, 0xbfb8aa3b, v71
	v_mul_f32_e32 v61, 0xbfb8aa3b, v61
	v_mul_f32_e32 v74, 0xbfb8aa3b, v74
	v_mul_f32_e32 v62, 0xbfb8aa3b, v62
	v_mul_f32_e32 v75, 0xbfb8aa3b, v75
	v_exp_f32_e32 v63, v63
	v_exp_f32_e32 v70, v70
	v_exp_f32_e32 v60, v60
	v_exp_f32_e32 v71, v71
	v_exp_f32_e32 v61, v61
	v_exp_f32_e32 v74, v74
	v_exp_f32_e32 v62, v62
	v_exp_f32_e32 v75, v75
	v_add_f32_e32 v63, 1.0, v63
	v_add_f32_e32 v70, 1.0, v70
	v_add_f32_e32 v60, 1.0, v60
	v_add_f32_e32 v71, 1.0, v71
	v_add_f32_e32 v61, 1.0, v61
	v_add_f32_e32 v74, 1.0, v74
	v_add_f32_e32 v62, 1.0, v62
	v_add_f32_e32 v75, 1.0, v75
	v_rcp_f32_e32 v63, v63
	v_rcp_f32_e32 v70, v70
	v_rcp_f32_e32 v60, v60
	v_rcp_f32_e32 v71, v71
	v_rcp_f32_e32 v61, v61
	v_rcp_f32_e32 v74, v74
	v_rcp_f32_e32 v62, v62
	v_rcp_f32_e32 v75, v75
	v_mul_f32_e32 v55, v55, v63
	v_mul_f32_e32 v56, v56, v70
	v_mul_f32_e32 v57, v57, v60
	v_mul_f32_e32 v58, v58, v71
	v_mul_f32_e32 v59, v59, v61
	v_mul_f32_e32 v60, v52, v74
	v_mul_f32_e32 v61, v53, v62
	v_mul_f32_e32 v62, v54, v75
	v_cvt_pk_bf16_f32 v52, v56, v57
	v_cvt_pk_bf16_f32 v53, v58, v59
	v_cvt_pk_bf16_f32 v54, v60, v61
	v_cvt_pk_bf16_f32 v55, v62, v55
	global_store_dwordx4 v[72:73], v[52:55], off offset:256
	global_load_dwordx4 v[52:55], v[68:69], off
	v_lshlrev_b64 v[56:57], 12, v[64:65]
	v_lshl_add_u64 v[56:57], s[38:39], 0, v[56:57]
	v_lshl_add_u64 v[56:57], v[56:57], 0, v[148:149]
	v_lshl_add_u64 v[58:59], v[66:67], 0, v[2:3]
	s_waitcnt vmcnt(0)
	v_lshlrev_b32_e32 v63, 16, v55
	v_and_b32_e32 v55, 0xffff0000, v55
	v_lshlrev_b32_e32 v60, 16, v52
	v_and_b32_e32 v52, 0xffff0000, v52
	v_lshlrev_b32_e32 v61, 16, v53
	v_and_b32_e32 v53, 0xffff0000, v53
	v_lshlrev_b32_e32 v62, 16, v54
	v_and_b32_e32 v54, 0xffff0000, v54
	v_med3_f32 v55, v55, s73, v159
	v_med3_f32 v60, v60, s73, v159
	v_med3_f32 v52, v52, s73, v159
	v_med3_f32 v61, v61, s73, v159
	v_med3_f32 v53, v53, s73, v159
	v_med3_f32 v62, v62, s73, v159
	v_med3_f32 v54, v54, s73, v159
	v_med3_f32 v63, v63, s73, v159
	v_mul_f32_e32 v55, 0xbfb8aa3b, v55
	v_mul_f32_e32 v60, 0xbfb8aa3b, v60
	v_mul_f32_e32 v52, 0xbfb8aa3b, v52
	v_mul_f32_e32 v61, 0xbfb8aa3b, v61
	v_mul_f32_e32 v53, 0xbfb8aa3b, v53
	v_mul_f32_e32 v62, 0xbfb8aa3b, v62
	v_mul_f32_e32 v54, 0xbfb8aa3b, v54
	v_mul_f32_e32 v63, 0xbfb8aa3b, v63
	v_exp_f32_e32 v55, v55
	v_exp_f32_e32 v60, v60
	v_exp_f32_e32 v52, v52
	v_exp_f32_e32 v61, v61
	v_exp_f32_e32 v53, v53
	v_exp_f32_e32 v62, v62
	v_exp_f32_e32 v54, v54
	v_exp_f32_e32 v63, v63
	v_add_f32_e32 v55, 1.0, v55
	v_add_f32_e32 v60, 1.0, v60
	v_add_f32_e32 v52, 1.0, v52
	v_add_f32_e32 v61, 1.0, v61
	v_add_f32_e32 v53, 1.0, v53
	v_add_f32_e32 v62, 1.0, v62
	v_add_f32_e32 v54, 1.0, v54
	v_add_f32_e32 v63, 1.0, v63
	v_rcp_f32_e32 v55, v55
	v_rcp_f32_e32 v60, v60
	v_rcp_f32_e32 v52, v52
	v_rcp_f32_e32 v61, v61
	v_rcp_f32_e32 v53, v53
	v_rcp_f32_e32 v62, v62
	v_rcp_f32_e32 v54, v54
	v_rcp_f32_e32 v63, v63
	v_mul_f32_e32 v47, v47, v55
	v_mul_f32_e32 v48, v48, v60
	v_mul_f32_e32 v49, v49, v52
	v_mul_f32_e32 v50, v50, v61
	v_mul_f32_e32 v51, v51, v53
	v_mul_f32_e32 v52, v44, v62
	v_mul_f32_e32 v53, v45, v54
	v_mul_f32_e32 v54, v46, v63
	v_cvt_pk_bf16_f32 v44, v48, v49
	v_cvt_pk_bf16_f32 v45, v50, v51
	v_cvt_pk_bf16_f32 v46, v52, v53
	v_cvt_pk_bf16_f32 v47, v54, v47
	global_store_dwordx4 v[56:57], v[44:47], off
	global_load_dwordx4 v[44:47], v[58:59], off
	v_add_u32_e32 v48, 0xa0, v150
	v_ashrrev_i32_e32 v49, 31, v48
	v_lshlrev_b64 v[50:51], 11, v[48:49]
	v_lshl_add_u64 v[50:51], s[46:47], 0, v[50:51]
	v_lshl_add_u64 v[52:53], v[50:51], 0, v[0:1]
	s_waitcnt vmcnt(0)
; __device__ __forceinline__ unsigned cvt_pk_bf16(float lo, float hi) { unsigned r; asm volatile("v_cvt_pk_bf16_f32 %0, %1, %2" : "=v"(r) : "v"(lo), "v"(hi)); return r; }
; __device__ __forceinline__ float bflo(unsigned w) { return __uint_as_float(w << 16); }
; __device__ __forceinline__ float bfhi(unsigned w) { return __uint_as_float(w & 0xffff0000u); }
; __device__ __forceinline__ float sigmoidf_(float x) { return __builtin_amdgcn_rcpf(1.f + __expf(-x)); }
;     static __device__ __forceinline__ float cl(float x) { return fminf(fmaxf(x, -30.f), 30.f); }
;     __device__ __forceinline__ void operator()(const f32x4 (&acc)[2][2][4][2], const Unit& u, int wr, int wc, int fr, int fq) const {
;     ...
;             for (int m = 0; m < 4; ++m) { const size_t row = (size_t)(row0 + ai * HALF + m * 16);
; #pragma unroll
;                 for (int bj = 0; bj < 2; ++bj) { const int col = u.pn * BM + bj * HALF + wc * 32 + 8 * fq;
;                     const u32x4 gw = *(const u32x4*)(gate + (size_t)(2 + (col >> 10)) * SEC + row * 1024 + (col & 1023));
;                     const f32x4 v0 = acc[ai][bj][m][0], v1 = acc[ai][bj][m][1];
;                     float r[8];
;                     r[0] = v0[0] * sigmoidf_(cl(bflo(gw.x))); r[1] = v0[1] * sigmoidf_(cl(bfhi(gw.x))); r[2] = v0[2] * sigmoidf_(cl(bflo(gw.y))); r[3] = v0[3] * sigmoidf_(cl(bfhi(gw.y)));
;                     r[4] = v1[0] * sigmoidf_(cl(bflo(gw.z))); r[5] = v1[1] * sigmoidf_(cl(bfhi(gw.z))); r[6] = v1[2] * sigmoidf_(cl(bflo(gw.w))); r[7] = v1[3] * sigmoidf_(cl(bfhi(gw.w)));
;                     u32x4 w; w.x = cvt_pk_bf16(r[0], r[1]); w.y = cvt_pk_bf16(r[2], r[3]); w.z = cvt_pk_bf16(r[4], r[5]); w.w = cvt_pk_bf16(r[6], r[7]);
;                     *(u32x4*)(mix + row * 2048 + col) = w; } }
	v_lshlrev_b32_e32 v59, 16, v47
	v_and_b32_e32 v47, 0xffff0000, v47
	v_lshlrev_b32_e32 v54, 16, v44
	v_and_b32_e32 v44, 0xffff0000, v44
	v_lshlrev_b32_e32 v55, 16, v45
	v_and_b32_e32 v45, 0xffff0000, v45
	v_lshlrev_b32_e32 v58, 16, v46
	v_and_b32_e32 v46, 0xffff0000, v46
	v_med3_f32 v47, v47, s73, v159
	v_med3_f32 v54, v54, s73, v159
	v_med3_f32 v44, v44, s73, v159
	v_med3_f32 v55, v55, s73, v159
	v_med3_f32 v45, v45, s73, v159
	v_med3_f32 v58, v58, s73, v159
	v_med3_f32 v46, v46, s73, v159
	v_med3_f32 v59, v59, s73, v159
	v_mul_f32_e32 v47, 0xbfb8aa3b, v47
	v_mul_f32_e32 v54, 0xbfb8aa3b, v54
	v_mul_f32_e32 v44, 0xbfb8aa3b, v44
	v_mul_f32_e32 v55, 0xbfb8aa3b, v55
	v_mul_f32_e32 v45, 0xbfb8aa3b, v45
	v_mul_f32_e32 v58, 0xbfb8aa3b, v58
	v_mul_f32_e32 v46, 0xbfb8aa3b, v46
	v_mul_f32_e32 v59, 0xbfb8aa3b, v59
	v_exp_f32_e32 v47, v47
	v_exp_f32_e32 v54, v54
	v_exp_f32_e32 v44, v44
	v_exp_f32_e32 v55, v55
	v_exp_f32_e32 v45, v45
	v_exp_f32_e32 v58, v58
	v_exp_f32_e32 v46, v46
	v_exp_f32_e32 v59, v59
	v_add_f32_e32 v47, 1.0, v47
	v_add_f32_e32 v54, 1.0, v54
	v_add_f32_e32 v44, 1.0, v44
	v_add_f32_e32 v55, 1.0, v55
	v_add_f32_e32 v45, 1.0, v45
	v_add_f32_e32 v58, 1.0, v58
	v_add_f32_e32 v46, 1.0, v46
	v_add_f32_e32 v59, 1.0, v59
	v_rcp_f32_e32 v47, v47
	v_rcp_f32_e32 v54, v54
	v_rcp_f32_e32 v44, v44
	v_rcp_f32_e32 v55, v55
	v_rcp_f32_e32 v45, v45
	v_rcp_f32_e32 v58, v58
	v_rcp_f32_e32 v46, v46
	v_rcp_f32_e32 v59, v59
	v_mul_f32_e32 v39, v39, v47
	v_mul_f32_e32 v40, v40, v54
	v_mul_f32_e32 v41, v41, v44
	v_mul_f32_e32 v42, v42, v55
	v_mul_f32_e32 v43, v43, v45
	v_mul_f32_e32 v44, v36, v58
	v_mul_f32_e32 v45, v37, v46
	v_mul_f32_e32 v46, v38, v59
	v_cvt_pk_bf16_f32 v36, v40, v41
	v_cvt_pk_bf16_f32 v37, v42, v43
	v_cvt_pk_bf16_f32 v38, v44, v45
	v_cvt_pk_bf16_f32 v39, v46, v39
	global_store_dwordx4 v[56:57], v[36:39], off offset:256
	global_load_dwordx4 v[36:39], v[52:53], off
	v_lshlrev_b64 v[40:41], 12, v[48:49]
	v_lshl_add_u64 v[40:41], s[38:39], 0, v[40:41]
	v_lshl_add_u64 v[40:41], v[40:41], 0, v[148:149]
	v_lshl_add_u64 v[42:43], v[50:51], 0, v[2:3]
	s_waitcnt vmcnt(0)
	v_lshlrev_b32_e32 v47, 16, v39
	v_and_b32_e32 v39, 0xffff0000, v39
	v_lshlrev_b32_e32 v44, 16, v36
	v_and_b32_e32 v36, 0xffff0000, v36
	v_lshlrev_b32_e32 v45, 16, v37
	v_and_b32_e32 v37, 0xffff0000, v37
	v_lshlrev_b32_e32 v46, 16, v38
	v_and_b32_e32 v38, 0xffff0000, v38
	v_med3_f32 v39, v39, s73, v159
	v_med3_f32 v44, v44, s73, v159
	v_med3_f32 v36, v36, s73, v159
	v_med3_f32 v45, v45, s73, v159
	v_med3_f32 v37, v37, s73, v159
	v_med3_f32 v46, v46, s73, v159
	v_med3_f32 v38, v38, s73, v159
	v_med3_f32 v47, v47, s73, v159
	v_mul_f32_e32 v39, 0xbfb8aa3b, v39
	v_mul_f32_e32 v44, 0xbfb8aa3b, v44
	v_mul_f32_e32 v36, 0xbfb8aa3b, v36
	v_mul_f32_e32 v45, 0xbfb8aa3b, v45
	v_mul_f32_e32 v37, 0xbfb8aa3b, v37
	v_mul_f32_e32 v46, 0xbfb8aa3b, v46
	v_mul_f32_e32 v38, 0xbfb8aa3b, v38
	v_mul_f32_e32 v47, 0xbfb8aa3b, v47
	v_exp_f32_e32 v39, v39
	v_exp_f32_e32 v44, v44
	v_exp_f32_e32 v36, v36
	v_exp_f32_e32 v45, v45
	v_exp_f32_e32 v37, v37
	v_exp_f32_e32 v46, v46
	v_exp_f32_e32 v38, v38
	v_exp_f32_e32 v47, v47
	v_add_f32_e32 v39, 1.0, v39
	v_add_f32_e32 v44, 1.0, v44
	v_add_f32_e32 v36, 1.0, v36
	v_add_f32_e32 v45, 1.0, v45
	v_add_f32_e32 v37, 1.0, v37
	v_add_f32_e32 v46, 1.0, v46
	v_add_f32_e32 v38, 1.0, v38
	v_add_f32_e32 v47, 1.0, v47
	v_rcp_f32_e32 v39, v39
	v_rcp_f32_e32 v44, v44
	v_rcp_f32_e32 v36, v36
	v_rcp_f32_e32 v45, v45
	v_rcp_f32_e32 v37, v37
	v_rcp_f32_e32 v46, v46
	v_rcp_f32_e32 v38, v38
	v_rcp_f32_e32 v47, v47
	v_mul_f32_e32 v31, v31, v39
	v_mul_f32_e32 v32, v32, v44
	v_mul_f32_e32 v33, v33, v36
	v_mul_f32_e32 v34, v34, v45
	v_mul_f32_e32 v35, v35, v37
	v_mul_f32_e32 v36, v28, v46
	v_mul_f32_e32 v37, v29, v38
	v_mul_f32_e32 v38, v30, v47
	v_cvt_pk_bf16_f32 v28, v32, v33
	v_cvt_pk_bf16_f32 v29, v34, v35
	v_cvt_pk_bf16_f32 v30, v36, v37
	v_cvt_pk_bf16_f32 v31, v38, v31
	global_store_dwordx4 v[40:41], v[28:31], off
	global_load_dwordx4 v[28:31], v[42:43], off
	v_add_u32_e32 v32, 0xb0, v150
	v_ashrrev_i32_e32 v33, 31, v32
	v_lshlrev_b64 v[34:35], 11, v[32:33]
	v_lshl_add_u64 v[34:35], s[46:47], 0, v[34:35]
	v_lshl_add_u64 v[36:37], v[34:35], 0, v[0:1]
	v_lshl_add_u64 v[2:3], v[34:35], 0, v[2:3]
	s_waitcnt vmcnt(0)
; __device__ __forceinline__ unsigned cvt_pk_bf16(float lo, float hi) { unsigned r; asm volatile("v_cvt_pk_bf16_f32 %0, %1, %2" : "=v"(r) : "v"(lo), "v"(hi)); return r; }
; __device__ __forceinline__ float bflo(unsigned w) { return __uint_as_float(w << 16); }
; __device__ __forceinline__ float bfhi(unsigned w) { return __uint_as_float(w & 0xffff0000u); }
; #define PG8_BAR __builtin_amdgcn_s_barrier()
;     __device__ __forceinline__ void operator()(const f32x4 (&acc)[2][2][4][2], const Unit& u, int wr, int wc, int fr, int fq) const {
;     ...
;             for (int m = 0; m < 4; ++m) { const size_t row = (size_t)(row0 + ai * HALF + m * 16);
; #pragma unroll
;                 for (int bj = 0; bj < 2; ++bj) { const int col = u.pn * BM + bj * HALF + wc * 32 + 8 * fq;
;                     const u32x4 gw = *(const u32x4*)(gate + (size_t)(2 + (col >> 10)) * SEC + row * 1024 + (col & 1023));
;                     const f32x4 v0 = acc[ai][bj][m][0], v1 = acc[ai][bj][m][1];
;                     float r[8];
;                     r[0] = v0[0] * sigmoidf_(cl(bflo(gw.x))); r[1] = v0[1] * sigmoidf_(cl(bfhi(gw.x))); r[2] = v0[2] * sigmoidf_(cl(bflo(gw.y))); r[3] = v0[3] * sigmoidf_(cl(bfhi(gw.y)));
;                     r[4] = v1[0] * sigmoidf_(cl(bflo(gw.z))); r[5] = v1[1] * sigmoidf_(cl(bfhi(gw.z))); r[6] = v1[2] * sigmoidf_(cl(bflo(gw.w))); r[7] = v1[3] * sigmoidf_(cl(bfhi(gw.w)));
;                     u32x4 w; w.x = cvt_pk_bf16(r[0], r[1]); w.y = cvt_pk_bf16(r[2], r[3]); w.z = cvt_pk_bf16(r[4], r[5]); w.w = cvt_pk_bf16(r[6], r[7]);
;                     *(u32x4*)(mix + row * 2048 + col) = w; } }
;     }
; template <class Epi, class Sched, bool ALIGN_EPI = false, bool SP2 = false>
; __device__ __forceinline__ void gemm_phase(PG8_LAS unsigned char* lds, const Gemm g, const Sched& S, const Epi& E) {
;     ...
;         if constexpr (ALIGN_EPI) { if (wr == 0) PG8_BAR; }
;         if constexpr (!Epi::AFTER_DRAIN) { E(acc, cur, wr, wc, fr, fq); S.done(cur); }
;         if (!has_next) break;
; #pragma unroll
;         for (int a = 0; a < 2; ++a)
; #pragma unroll
;             for (int b = 0; b < 2; ++b)
; #pragma unroll
;                 for (int m = 0; m < 4; ++m)
; #pragma unroll
;                     for (int n = 0; n < 2; ++n) acc[a][b][m][n] = (f32x4){0.f, 0.f, 0.f, 0.f};
;         cur = nxt; cA = nA; cB = nB; ++ui;
;         if constexpr (ALIGN_EPI) { if (wr == 1) PG8_BAR; }
	v_lshlrev_b32_e32 v42, 16, v31
	v_and_b32_e32 v31, 0xffff0000, v31
	v_lshlrev_b32_e32 v0, 16, v28
	v_and_b32_e32 v28, 0xffff0000, v28
	v_lshlrev_b32_e32 v38, 16, v29
	v_and_b32_e32 v29, 0xffff0000, v29
	v_lshlrev_b32_e32 v39, 16, v30
	v_and_b32_e32 v30, 0xffff0000, v30
	v_med3_f32 v31, v31, s73, v159
	v_med3_f32 v0, v0, s73, v159
	v_med3_f32 v28, v28, s73, v159
	v_med3_f32 v38, v38, s73, v159
	v_med3_f32 v29, v29, s73, v159
	v_med3_f32 v39, v39, s73, v159
	v_med3_f32 v30, v30, s73, v159
	v_med3_f32 v42, v42, s73, v159
	v_mul_f32_e32 v31, 0xbfb8aa3b, v31
	v_mul_f32_e32 v0, 0xbfb8aa3b, v0
	v_mul_f32_e32 v28, 0xbfb8aa3b, v28
	v_mul_f32_e32 v38, 0xbfb8aa3b, v38
	v_mul_f32_e32 v29, 0xbfb8aa3b, v29
	v_mul_f32_e32 v39, 0xbfb8aa3b, v39
	v_mul_f32_e32 v30, 0xbfb8aa3b, v30
	v_mul_f32_e32 v42, 0xbfb8aa3b, v42
	v_exp_f32_e32 v31, v31
	v_exp_f32_e32 v0, v0
	v_exp_f32_e32 v28, v28
	v_exp_f32_e32 v38, v38
	v_exp_f32_e32 v29, v29
	v_exp_f32_e32 v39, v39
	v_exp_f32_e32 v30, v30
	v_exp_f32_e32 v42, v42
	v_add_f32_e32 v31, 1.0, v31
	v_add_f32_e32 v0, 1.0, v0
	v_add_f32_e32 v28, 1.0, v28
	v_add_f32_e32 v38, 1.0, v38
	v_add_f32_e32 v29, 1.0, v29
	v_add_f32_e32 v39, 1.0, v39
	v_add_f32_e32 v30, 1.0, v30
	v_add_f32_e32 v42, 1.0, v42
	v_rcp_f32_e32 v31, v31
	v_rcp_f32_e32 v0, v0
	v_rcp_f32_e32 v28, v28
	v_rcp_f32_e32 v38, v38
	v_rcp_f32_e32 v29, v29
	v_rcp_f32_e32 v39, v39
	v_rcp_f32_e32 v30, v30
	v_rcp_f32_e32 v42, v42
	v_mul_f32_e32 v23, v23, v31
	v_mul_f32_e32 v0, v24, v0
	v_mul_f32_e32 v24, v25, v28
	v_mul_f32_e32 v25, v26, v38
	v_mul_f32_e32 v26, v27, v29
	v_mul_f32_e32 v27, v20, v39
	v_mul_f32_e32 v28, v21, v30
	v_mul_f32_e32 v29, v22, v42
	v_cvt_pk_bf16_f32 v20, v0, v24
	v_cvt_pk_bf16_f32 v21, v25, v26
	v_cvt_pk_bf16_f32 v22, v27, v28
	v_cvt_pk_bf16_f32 v23, v29, v23
	global_store_dwordx4 v[40:41], v[20:23], off offset:256
	global_load_dwordx4 v[20:23], v[36:37], off
	v_lshlrev_b64 v[24:25], 12, v[32:33]
	v_lshl_add_u64 v[24:25], s[38:39], 0, v[24:25]
	v_lshl_add_u64 v[24:25], v[24:25], 0, v[148:149]
	s_waitcnt vmcnt(0)
	v_lshlrev_b32_e32 v28, 16, v23
	v_and_b32_e32 v23, 0xffff0000, v23
	v_lshlrev_b32_e32 v0, 16, v20
	v_and_b32_e32 v20, 0xffff0000, v20
	v_lshlrev_b32_e32 v26, 16, v21
	v_and_b32_e32 v21, 0xffff0000, v21
	v_lshlrev_b32_e32 v27, 16, v22
	v_and_b32_e32 v22, 0xffff0000, v22
	v_med3_f32 v23, v23, s73, v159
	v_med3_f32 v0, v0, s73, v159
	v_med3_f32 v20, v20, s73, v159
	v_med3_f32 v26, v26, s73, v159
	v_med3_f32 v21, v21, s73, v159
	v_med3_f32 v27, v27, s73, v159
	v_med3_f32 v22, v22, s73, v159
	v_med3_f32 v28, v28, s73, v159
	v_mul_f32_e32 v23, 0xbfb8aa3b, v23
	v_mul_f32_e32 v0, 0xbfb8aa3b, v0
	v_mul_f32_e32 v20, 0xbfb8aa3b, v20
	v_mul_f32_e32 v26, 0xbfb8aa3b, v26
	v_mul_f32_e32 v21, 0xbfb8aa3b, v21
	v_mul_f32_e32 v27, 0xbfb8aa3b, v27
	v_mul_f32_e32 v22, 0xbfb8aa3b, v22
	v_mul_f32_e32 v28, 0xbfb8aa3b, v28
	v_exp_f32_e32 v23, v23
	v_exp_f32_e32 v0, v0
	v_exp_f32_e32 v20, v20
	v_exp_f32_e32 v26, v26
	v_exp_f32_e32 v21, v21
	v_exp_f32_e32 v27, v27
	v_exp_f32_e32 v22, v22
	v_exp_f32_e32 v28, v28
	v_add_f32_e32 v23, 1.0, v23
	v_add_f32_e32 v0, 1.0, v0
	v_add_f32_e32 v20, 1.0, v20
	v_add_f32_e32 v26, 1.0, v26
	v_add_f32_e32 v21, 1.0, v21
	v_add_f32_e32 v27, 1.0, v27
	v_add_f32_e32 v22, 1.0, v22
	v_add_f32_e32 v28, 1.0, v28
	v_rcp_f32_e32 v23, v23
	v_rcp_f32_e32 v0, v0
	v_rcp_f32_e32 v20, v20
	v_rcp_f32_e32 v26, v26
	v_rcp_f32_e32 v21, v21
	v_rcp_f32_e32 v27, v27
	v_rcp_f32_e32 v22, v22
	v_rcp_f32_e32 v28, v28
	v_mul_f32_e32 v15, v15, v23
	v_mul_f32_e32 v0, v16, v0
	v_mul_f32_e32 v16, v17, v20
	v_mul_f32_e32 v17, v18, v26
	v_mul_f32_e32 v18, v19, v21
	v_mul_f32_e32 v19, v12, v27
	v_mul_f32_e32 v20, v13, v22
	v_mul_f32_e32 v21, v14, v28
	v_cvt_pk_bf16_f32 v12, v0, v16
	v_cvt_pk_bf16_f32 v13, v17, v18
	v_cvt_pk_bf16_f32 v14, v19, v20
	v_cvt_pk_bf16_f32 v15, v21, v15
	global_store_dwordx4 v[24:25], v[12:15], off
	global_load_dwordx4 v[12:15], v[2:3], off
	s_waitcnt vmcnt(0)
	v_lshlrev_b32_e32 v0, 16, v12
	v_and_b32_e32 v2, 0xffff0000, v12
	v_lshlrev_b32_e32 v3, 16, v13
	v_and_b32_e32 v12, 0xffff0000, v13
	v_lshlrev_b32_e32 v13, 16, v14
	v_and_b32_e32 v14, 0xffff0000, v14
	v_lshlrev_b32_e32 v16, 16, v15
	v_and_b32_e32 v15, 0xffff0000, v15
	v_med3_f32 v2, v2, s73, v159
	v_med3_f32 v3, v3, s73, v159
	v_med3_f32 v13, v13, s73, v159
	v_med3_f32 v14, v14, s73, v159
	v_med3_f32 v0, v0, s73, v159
	v_med3_f32 v12, v12, s73, v159
	v_med3_f32 v16, v16, s73, v159
	v_med3_f32 v15, v15, s73, v159
	v_mul_f32_e32 v2, 0xbfb8aa3b, v2
	v_mul_f32_e32 v3, 0xbfb8aa3b, v3
	v_mul_f32_e32 v13, 0xbfb8aa3b, v13
	v_mul_f32_e32 v14, 0xbfb8aa3b, v14
	v_mul_f32_e32 v0, 0xbfb8aa3b, v0
	v_mul_f32_e32 v12, 0xbfb8aa3b, v12
	v_mul_f32_e32 v16, 0xbfb8aa3b, v16
	v_mul_f32_e32 v15, 0xbfb8aa3b, v15
	v_exp_f32_e32 v2, v2
	v_exp_f32_e32 v3, v3
	v_exp_f32_e32 v13, v13
	v_exp_f32_e32 v14, v14
	v_exp_f32_e32 v0, v0
	v_exp_f32_e32 v12, v12
	v_exp_f32_e32 v16, v16
	v_exp_f32_e32 v15, v15
	v_add_f32_e32 v2, 1.0, v2
	v_add_f32_e32 v3, 1.0, v3
	v_add_f32_e32 v13, 1.0, v13
	v_add_f32_e32 v14, 1.0, v14
	v_add_f32_e32 v0, 1.0, v0
	v_add_f32_e32 v12, 1.0, v12
	v_add_f32_e32 v16, 1.0, v16
	v_add_f32_e32 v15, 1.0, v15
	v_rcp_f32_e32 v2, v2
	v_rcp_f32_e32 v3, v3
	v_rcp_f32_e32 v13, v13
	v_rcp_f32_e32 v14, v14
	v_rcp_f32_e32 v0, v0
	v_rcp_f32_e32 v12, v12
	v_rcp_f32_e32 v16, v16
	v_rcp_f32_e32 v15, v15
	v_mul_f32_e32 v2, v9, v2
	v_mul_f32_e32 v3, v10, v3
	v_mul_f32_e32 v4, v4, v13
	v_mul_f32_e32 v5, v5, v14
	v_mul_f32_e32 v0, v8, v0
	v_mul_f32_e32 v8, v11, v12
	v_mul_f32_e32 v6, v6, v16
	v_mul_f32_e32 v7, v7, v15
	v_cvt_pk_bf16_f32 v2, v0, v2
	v_cvt_pk_bf16_f32 v3, v3, v8
	v_cvt_pk_bf16_f32 v4, v4, v5
	v_cvt_pk_bf16_f32 v5, v6, v7
	global_store_dwordx4 v[24:25], v[2:5], off offset:256
	s_cbranch_vccnz .LBB0_619
	s_andn2_b64 vcc, exec, s[6:7]
	s_cbranch_vccnz .LBB0_618
	s_barrier
	s_branch .LBB0_618
